# E35: EpiRmw<0> epilogues (FFN1-out, mixer-out, FFN2-out) issue the x-tile loads of all four row stages up front into dead fragment VGPRs (SADDR form), vmcnt waits re-counted; on E28
# baseline (speedup 1.0000x reference)
.LBB0_583:
	s_lshl_b32 s8, s12, 8
	s_add_i32 s46, s8, s31
	s_lshl_b32 s2, s2, 8
	s_ashr_i32 s47, s46, 31
	s_or_b32 s8, s2, s33
	s_lshl_b64 s[12:13], s[46:47], 12
	s_add_u32 s2, s34, s12
	s_addc_u32 s12, s35, s13
	s_ashr_i32 s9, s8, 31
	s_lshl_b64 s[8:9], s[8:9], 1
	s_add_u32 s26, s2, s8
	s_addc_u32 s27, s12, s9
	global_load_dwordx4 v[142:145], v146, s[26:27]
	global_load_dwordx4 v[170:173], v146, s[26:27] offset:256
	v_lshl_add_u64 v[132:133], s[26:27], 0, v[146:147]
	v_add_co_u32_e32 v134, vcc, s53, v132
	s_mov_b32 s2, 0x30000
	s_nop 0
	v_addc_co_u32_e32 v135, vcc, 0, v133, vcc
	global_load_dwordx4 v[174:177], v[134:135], off
	global_load_dwordx4 v[178:181], v[134:135], off offset:256
	s_add_u32 s12, s26, 0x30000
	s_addc_u32 s13, s27, 0
	global_load_dwordx4 v[182:185], v146, s[12:13] offset:256
	global_load_dwordx4 v[186:189], v146, s[12:13]
	s_add_u32 s12, s26, s63
	s_addc_u32 s13, s27, 0
	global_load_dwordx4 v[190:193], v146, s[12:13] offset:256
	global_load_dwordx4 v[194:197], v146, s[12:13]
	s_add_u32 s12, s26, 0x90000
	s_addc_u32 s13, s27, 0
	global_load_dwordx4 v[198:201], v146, s[12:13] offset:256
	global_load_dwordx4 v[202:205], v146, s[12:13]
	s_add_u32 s12, s26, 0x80000
	s_addc_u32 s13, s27, 0
	global_load_dwordx4 v[228:231], v146, s[12:13] offset:256
	global_load_dwordx4 v[232:235], v146, s[12:13]
	s_add_u32 s12, s26, 0xb0000
	s_addc_u32 s13, s27, 0
	global_load_dwordx4 v[236:239], v146, s[12:13] offset:256
	global_load_dwordx4 v[240:243], v146, s[12:13]
	s_add_u32 s12, s26, 0xa0000
	s_addc_u32 s13, s27, 0
	global_load_dwordx4 v[244:247], v146, s[12:13] offset:256
	global_load_dwordx4 v[248:251], v146, s[12:13]
	s_waitcnt vmcnt(12)
	v_lshlrev_b32_e32 v154, 16, v142
	v_and_b32_e32 v155, 0xffff0000, v142
	v_lshlrev_b32_e32 v142, 16, v143
	v_and_b32_e32 v143, 0xffff0000, v143
	v_lshlrev_b32_e32 v156, 16, v144
	v_and_b32_e32 v157, 0xffff0000, v144
	v_lshlrev_b32_e32 v144, 16, v145
	v_and_b32_e32 v145, 0xffff0000, v145
	v_pk_fma_f32 v[128:129], v[128:129], 0.5, v[142:143] op_sel_hi:[1,0,1]
	v_pk_fma_f32 v[126:127], v[126:127], 0.5, v[154:155] op_sel_hi:[1,0,1]
	v_pk_fma_f32 v[142:143], v[108:109], 0.5, v[144:145] op_sel_hi:[1,0,1]
	v_pk_fma_f32 v[108:109], v[106:107], 0.5, v[156:157] op_sel_hi:[1,0,1]
	v_mul_f32_e32 v106, v127, v127
	v_mul_f32_e32 v107, v129, v129
	v_fmac_f32_e32 v106, v126, v126
	v_fmac_f32_e32 v107, v128, v128
	v_add_f32_e32 v106, v106, v107
	v_mul_f32_e32 v107, v109, v109
	v_fmac_f32_e32 v107, v108, v108
	v_add_f32_e32 v106, v107, v106
	v_mul_f32_e32 v107, v143, v143
	v_fmac_f32_e32 v107, v142, v142
	v_add_f32_e32 v154, v107, v106
	v_cvt_pk_bf16_f32 v106, v126, v127
	v_cvt_pk_bf16_f32 v107, v128, v129
	s_waitcnt vmcnt(14)
	v_lshlrev_b32_e32 v126, 16, v170
	v_and_b32_e32 v127, 0xffff0000, v170
	v_lshlrev_b32_e32 v128, 16, v171
	v_and_b32_e32 v129, 0xffff0000, v171
	v_cvt_pk_bf16_f32 v108, v108, v109
	v_cvt_pk_bf16_f32 v109, v142, v143
	v_lshlrev_b32_e32 v142, 16, v172
	v_and_b32_e32 v143, 0xffff0000, v172
	v_lshlrev_b32_e32 v144, 16, v173
	v_and_b32_e32 v145, 0xffff0000, v173
	v_pk_fma_f32 v[124:125], v[124:125], 0.5, v[128:129] op_sel_hi:[1,0,1]
	v_pk_fma_f32 v[122:123], v[122:123], 0.5, v[126:127] op_sel_hi:[1,0,1]
	v_pk_fma_f32 v[126:127], v[112:113], 0.5, v[144:145] op_sel_hi:[1,0,1]
	v_pk_fma_f32 v[112:113], v[110:111], 0.5, v[142:143] op_sel_hi:[1,0,1]
	v_mul_f32_e32 v110, v123, v123
	v_mul_f32_e32 v111, v125, v125
	v_fmac_f32_e32 v110, v122, v122
	v_fmac_f32_e32 v111, v124, v124
	v_add_f32_e32 v110, v110, v111
	v_mul_f32_e32 v111, v113, v113
	v_fmac_f32_e32 v111, v112, v112
	v_add_f32_e32 v110, v111, v110
	v_mul_f32_e32 v111, v127, v127
	v_fmac_f32_e32 v111, v126, v126
	v_add_f32_e32 v110, v111, v110
	v_add_f32_e32 v128, v154, v110
	v_cvt_pk_bf16_f32 v110, v122, v123
	v_and_b32_e32 v123, 64, v222
	v_xor_b32_e32 v122, 16, v222
	v_add_u32_e32 v123, 64, v123
	v_cmp_lt_i32_e32 vcc, v122, v123
	v_cvt_pk_bf16_f32 v111, v124, v125
	s_waitcnt vmcnt(13)
	v_lshlrev_b32_e32 v124, 16, v175
	v_and_b32_e32 v125, 0xffff0000, v175
	v_cndmask_b32_e32 v122, v222, v122, vcc
	v_lshlrev_b32_e32 v145, 2, v122
	ds_bpermute_b32 v122, v145, v128
	v_cvt_pk_bf16_f32 v112, v112, v113
	v_cvt_pk_bf16_f32 v113, v126, v127
	v_lshlrev_b32_e32 v126, 16, v176
	v_and_b32_e32 v127, 0xffff0000, v176
	s_waitcnt lgkmcnt(0)
	v_add_f32_e32 v142, v128, v122
	v_xor_b32_e32 v122, 32, v222
	v_cmp_lt_i32_e32 vcc, v122, v123
	v_and_b32_e32 v123, 0xffff0000, v174
	v_lshlrev_b32_e32 v128, 16, v177
	v_cndmask_b32_e32 v122, v222, v122, vcc
	v_lshlrev_b32_e32 v144, 2, v122
	v_lshlrev_b32_e32 v122, 16, v174
	v_and_b32_e32 v129, 0xffff0000, v177
	v_pk_fma_f32 v[120:121], v[120:121], 0.5, v[124:125] op_sel_hi:[1,0,1]
	v_pk_fma_f32 v[118:119], v[118:119], 0.5, v[122:123] op_sel_hi:[1,0,1]
	v_pk_fma_f32 v[122:123], v[116:117], 0.5, v[128:129] op_sel_hi:[1,0,1]
	v_pk_fma_f32 v[116:117], v[114:115], 0.5, v[126:127] op_sel_hi:[1,0,1]
	v_mul_f32_e32 v114, v119, v119
	v_mul_f32_e32 v115, v121, v121
	v_fmac_f32_e32 v114, v118, v118
	v_fmac_f32_e32 v115, v120, v120
	v_add_f32_e32 v114, v114, v115
	v_mul_f32_e32 v115, v117, v117
	v_fmac_f32_e32 v115, v116, v116
	v_add_f32_e32 v114, v115, v114
	v_mul_f32_e32 v115, v123, v123
	v_fmac_f32_e32 v115, v122, v122
	v_add_f32_e32 v126, v115, v114
	v_cvt_pk_bf16_f32 v114, v118, v119
	v_cvt_pk_bf16_f32 v115, v120, v121
	s_waitcnt vmcnt(12)
	v_lshlrev_b32_e32 v118, 16, v178
	v_and_b32_e32 v119, 0xffff0000, v178
	v_lshlrev_b32_e32 v120, 16, v179
	v_and_b32_e32 v121, 0xffff0000, v179
	v_pk_fma_f32 v[104:105], v[104:105], 0.5, v[120:121] op_sel_hi:[1,0,1]
	v_pk_fma_f32 v[102:103], v[102:103], 0.5, v[118:119] op_sel_hi:[1,0,1]
	v_cvt_pk_bf16_f32 v116, v116, v117
	v_cvt_pk_bf16_f32 v117, v122, v123
	v_lshlrev_b32_e32 v122, 16, v180
	v_and_b32_e32 v123, 0xffff0000, v180
	v_mul_f32_e32 v118, v103, v103
	v_mul_f32_e32 v119, v105, v105
	v_pk_fma_f32 v[98:99], v[98:99], 0.5, v[122:123] op_sel_hi:[1,0,1]
	v_fmac_f32_e32 v118, v102, v102
	v_fmac_f32_e32 v119, v104, v104
	v_lshlrev_b32_e32 v124, 16, v181
	v_and_b32_e32 v125, 0xffff0000, v181
	v_add_f32_e32 v118, v118, v119
	v_mul_f32_e32 v119, v99, v99
	v_pk_fma_f32 v[100:101], v[100:101], 0.5, v[124:125] op_sel_hi:[1,0,1]
	v_fmac_f32_e32 v119, v98, v98
	v_add_f32_e32 v118, v119, v118
	v_mul_f32_e32 v119, v101, v101
	v_fmac_f32_e32 v119, v100, v100
	v_add_f32_e32 v118, v119, v118
	v_add_f32_e32 v122, v126, v118
	v_cvt_pk_bf16_f32 v118, v102, v103
	v_cvt_pk_bf16_f32 v119, v104, v105
	v_cvt_pk_bf16_f32 v120, v98, v99
	ds_bpermute_b32 v98, v145, v122
	v_add_co_u32_e32 v126, vcc, s2, v132
	v_cvt_pk_bf16_f32 v121, v100, v101
	s_mov_b32 s2, 0x90000
	s_nop 0
	v_addc_co_u32_e32 v127, vcc, 0, v133, vcc
	v_add_co_u32_e32 v128, vcc, s63, v132
	s_waitcnt lgkmcnt(0)
	v_add_f32_e32 v170, v122, v98
	v_addc_co_u32_e32 v129, vcc, 0, v133, vcc
	global_store_dwordx4 v146, v[106:109], s[26:27]
	global_store_dwordx4 v146, v[110:113], s[26:27] offset:256
	global_store_dwordx4 v[134:135], v[114:117], off
	global_store_dwordx4 v[134:135], v[118:121], off offset:256
	ds_bpermute_b32 v143, v144, v142
	ds_bpermute_b32 v171, v144, v170
	s_waitcnt vmcnt(12)
	v_lshlrev_b32_e32 v106, 16, v194
	v_and_b32_e32 v107, 0xffff0000, v194
	v_lshlrev_b32_e32 v108, 16, v195
	v_and_b32_e32 v109, 0xffff0000, v195
	v_lshlrev_b32_e32 v110, 16, v196
	v_and_b32_e32 v111, 0xffff0000, v196
	v_lshlrev_b32_e32 v112, 16, v197
	v_and_b32_e32 v113, 0xffff0000, v197
	v_pk_fma_f32 v[96:97], v[96:97], 0.5, v[108:109] op_sel_hi:[1,0,1]
	v_pk_fma_f32 v[94:95], v[94:95], 0.5, v[106:107] op_sel_hi:[1,0,1]
	v_pk_fma_f32 v[106:107], v[92:93], 0.5, v[112:113] op_sel_hi:[1,0,1]
	v_pk_fma_f32 v[92:93], v[90:91], 0.5, v[110:111] op_sel_hi:[1,0,1]
	v_mul_f32_e32 v90, v95, v95
	v_mul_f32_e32 v91, v97, v97
	v_fmac_f32_e32 v90, v94, v94
	v_fmac_f32_e32 v91, v96, v96
	v_add_f32_e32 v90, v90, v91
	v_mul_f32_e32 v91, v93, v93
	v_fmac_f32_e32 v91, v92, v92
	v_add_f32_e32 v90, v91, v90
	v_mul_f32_e32 v91, v107, v107
	v_fmac_f32_e32 v91, v106, v106
	v_add_f32_e32 v110, v91, v90
	v_cvt_pk_bf16_f32 v90, v94, v95
	v_cvt_pk_bf16_f32 v91, v96, v97
	v_lshlrev_b32_e32 v94, 16, v190
	v_and_b32_e32 v95, 0xffff0000, v190
	v_lshlrev_b32_e32 v96, 16, v191
	v_and_b32_e32 v97, 0xffff0000, v191
	v_cvt_pk_bf16_f32 v92, v92, v93
	v_cvt_pk_bf16_f32 v93, v106, v107
	v_lshlrev_b32_e32 v106, 16, v192
	v_and_b32_e32 v107, 0xffff0000, v192
	v_lshlrev_b32_e32 v108, 16, v193
	v_and_b32_e32 v109, 0xffff0000, v193
	v_pk_fma_f32 v[88:89], v[88:89], 0.5, v[96:97] op_sel_hi:[1,0,1]
	v_pk_fma_f32 v[86:87], v[86:87], 0.5, v[94:95] op_sel_hi:[1,0,1]
	v_pk_fma_f32 v[94:95], v[84:85], 0.5, v[108:109] op_sel_hi:[1,0,1]
	v_pk_fma_f32 v[84:85], v[82:83], 0.5, v[106:107] op_sel_hi:[1,0,1]
	v_mul_f32_e32 v82, v87, v87
	v_mul_f32_e32 v83, v89, v89
	v_fmac_f32_e32 v82, v86, v86
	v_fmac_f32_e32 v83, v88, v88
	v_add_f32_e32 v82, v82, v83
	v_mul_f32_e32 v83, v85, v85
	v_fmac_f32_e32 v83, v84, v84
	v_add_f32_e32 v82, v83, v82
	v_mul_f32_e32 v83, v95, v95
	v_fmac_f32_e32 v83, v94, v94
	v_add_f32_e32 v82, v83, v82
	v_add_f32_e32 v96, v82, v110
	v_cvt_pk_bf16_f32 v82, v86, v87
	ds_bpermute_b32 v86, v145, v96
	v_cvt_pk_bf16_f32 v83, v88, v89
	v_and_b32_e32 v87, 0xffff0000, v186
	v_lshlrev_b32_e32 v88, 16, v187
	v_and_b32_e32 v89, 0xffff0000, v187
	s_waitcnt lgkmcnt(0)
	v_add_f32_e32 v106, v96, v86
	v_lshlrev_b32_e32 v86, 16, v186
	v_cvt_pk_bf16_f32 v84, v84, v85
	v_cvt_pk_bf16_f32 v85, v94, v95
	v_lshlrev_b32_e32 v94, 16, v188
	v_and_b32_e32 v95, 0xffff0000, v188
	v_lshlrev_b32_e32 v96, 16, v189
	v_and_b32_e32 v97, 0xffff0000, v189
	v_pk_fma_f32 v[80:81], v[80:81], 0.5, v[88:89] op_sel_hi:[1,0,1]
	v_pk_fma_f32 v[78:79], v[78:79], 0.5, v[86:87] op_sel_hi:[1,0,1]
	v_pk_fma_f32 v[86:87], v[76:77], 0.5, v[96:97] op_sel_hi:[1,0,1]
	v_pk_fma_f32 v[76:77], v[74:75], 0.5, v[94:95] op_sel_hi:[1,0,1]
	v_mul_f32_e32 v74, v79, v79
	v_mul_f32_e32 v75, v81, v81
	v_fmac_f32_e32 v74, v78, v78
	v_fmac_f32_e32 v75, v80, v80
	v_add_f32_e32 v74, v74, v75
	v_mul_f32_e32 v75, v77, v77
	v_fmac_f32_e32 v75, v76, v76
	v_add_f32_e32 v74, v75, v74
	v_mul_f32_e32 v75, v87, v87
	v_fmac_f32_e32 v75, v86, v86
	v_add_f32_e32 v94, v75, v74
	v_cvt_pk_bf16_f32 v74, v78, v79
	v_cvt_pk_bf16_f32 v75, v80, v81
	v_lshlrev_b32_e32 v78, 16, v182
	v_and_b32_e32 v79, 0xffff0000, v182
	v_lshlrev_b32_e32 v80, 16, v183
	v_and_b32_e32 v81, 0xffff0000, v183
	v_pk_fma_f32 v[72:73], v[72:73], 0.5, v[80:81] op_sel_hi:[1,0,1]
	v_pk_fma_f32 v[70:71], v[70:71], 0.5, v[78:79] op_sel_hi:[1,0,1]
	v_cvt_pk_bf16_f32 v76, v76, v77
	v_cvt_pk_bf16_f32 v77, v86, v87
	v_lshlrev_b32_e32 v86, 16, v184
	v_and_b32_e32 v87, 0xffff0000, v184
	v_mul_f32_e32 v78, v71, v71
	v_mul_f32_e32 v79, v73, v73
	v_pk_fma_f32 v[66:67], v[66:67], 0.5, v[86:87] op_sel_hi:[1,0,1]
	v_fmac_f32_e32 v78, v70, v70
	v_fmac_f32_e32 v79, v72, v72
	v_lshlrev_b32_e32 v88, 16, v185
	v_and_b32_e32 v89, 0xffff0000, v185
	v_add_f32_e32 v78, v78, v79
	v_mul_f32_e32 v79, v67, v67
	v_pk_fma_f32 v[68:69], v[68:69], 0.5, v[88:89] op_sel_hi:[1,0,1]
	v_fmac_f32_e32 v79, v66, v66
	v_add_f32_e32 v78, v79, v78
	v_mul_f32_e32 v79, v69, v69
	v_fmac_f32_e32 v79, v68, v68
	v_add_f32_e32 v78, v79, v78
	v_add_f32_e32 v78, v78, v94
	v_cvt_pk_bf16_f32 v86, v70, v71
	v_cvt_pk_bf16_f32 v87, v72, v73
	v_cvt_pk_bf16_f32 v88, v66, v67
	ds_bpermute_b32 v66, v145, v78
	v_add_co_u32_e32 v98, vcc, s2, v132
	s_mov_b32 s2, 0x80000
	s_nop 0
	v_addc_co_u32_e32 v99, vcc, 0, v133, vcc
	v_add_co_u32_e32 v100, vcc, s2, v132
	v_cvt_pk_bf16_f32 v89, v68, v69
	s_waitcnt lgkmcnt(0)
	v_add_f32_e32 v102, v78, v66
	v_addc_co_u32_e32 v101, vcc, 0, v133, vcc
	global_store_dwordx4 v[128:129], v[90:93], off
	global_store_dwordx4 v[128:129], v[82:85], off offset:256
	global_store_dwordx4 v[126:127], v[74:77], off
	global_store_dwordx4 v[126:127], v[86:89], off offset:256
	s_mov_b32 s2, 0xb0000
	ds_bpermute_b32 v107, v144, v106
	ds_bpermute_b32 v103, v144, v102
	s_waitcnt vmcnt(12)
	v_lshlrev_b32_e32 v74, 16, v232
	v_and_b32_e32 v75, 0xffff0000, v232
	v_lshlrev_b32_e32 v76, 16, v233
	v_and_b32_e32 v77, 0xffff0000, v233
	v_lshlrev_b32_e32 v82, 16, v234
	v_and_b32_e32 v83, 0xffff0000, v234
	v_lshlrev_b32_e32 v84, 16, v235
	v_and_b32_e32 v85, 0xffff0000, v235
	v_pk_fma_f32 v[64:65], v[64:65], 0.5, v[76:77] op_sel_hi:[1,0,1]
	v_pk_fma_f32 v[62:63], v[62:63], 0.5, v[74:75] op_sel_hi:[1,0,1]
	v_pk_fma_f32 v[74:75], v[60:61], 0.5, v[84:85] op_sel_hi:[1,0,1]
	v_pk_fma_f32 v[60:61], v[58:59], 0.5, v[82:83] op_sel_hi:[1,0,1]
	v_mul_f32_e32 v58, v63, v63
	v_mul_f32_e32 v59, v65, v65
	v_fmac_f32_e32 v58, v62, v62
	v_fmac_f32_e32 v59, v64, v64
	v_add_f32_e32 v58, v58, v59
	v_mul_f32_e32 v59, v61, v61
	v_fmac_f32_e32 v59, v60, v60
	v_add_f32_e32 v58, v59, v58
	v_mul_f32_e32 v59, v75, v75
	v_fmac_f32_e32 v59, v74, v74
	v_add_f32_e32 v82, v59, v58
	v_cvt_pk_bf16_f32 v58, v62, v63
	v_cvt_pk_bf16_f32 v59, v64, v65
	v_lshlrev_b32_e32 v62, 16, v228
	v_and_b32_e32 v63, 0xffff0000, v228
	v_lshlrev_b32_e32 v64, 16, v229
	v_and_b32_e32 v65, 0xffff0000, v229
	v_cvt_pk_bf16_f32 v60, v60, v61
	v_cvt_pk_bf16_f32 v61, v74, v75
	v_lshlrev_b32_e32 v74, 16, v230
	v_and_b32_e32 v75, 0xffff0000, v230
	v_lshlrev_b32_e32 v76, 16, v231
	v_and_b32_e32 v77, 0xffff0000, v231
	v_pk_fma_f32 v[56:57], v[56:57], 0.5, v[64:65] op_sel_hi:[1,0,1]
	v_pk_fma_f32 v[54:55], v[54:55], 0.5, v[62:63] op_sel_hi:[1,0,1]
	v_pk_fma_f32 v[62:63], v[52:53], 0.5, v[76:77] op_sel_hi:[1,0,1]
	v_pk_fma_f32 v[52:53], v[50:51], 0.5, v[74:75] op_sel_hi:[1,0,1]
	v_mul_f32_e32 v50, v55, v55
	v_mul_f32_e32 v51, v57, v57
	v_fmac_f32_e32 v50, v54, v54
	v_fmac_f32_e32 v51, v56, v56
	v_add_f32_e32 v50, v50, v51
	v_mul_f32_e32 v51, v53, v53
	v_fmac_f32_e32 v51, v52, v52
	v_add_f32_e32 v50, v51, v50
	v_mul_f32_e32 v51, v63, v63
	v_fmac_f32_e32 v51, v62, v62
	v_add_f32_e32 v50, v51, v50
	v_add_f32_e32 v64, v50, v82
	v_cvt_pk_bf16_f32 v50, v54, v55
	ds_bpermute_b32 v54, v145, v64
	v_cvt_pk_bf16_f32 v51, v56, v57
	v_and_b32_e32 v55, 0xffff0000, v202
	v_lshlrev_b32_e32 v56, 16, v203
	v_and_b32_e32 v57, 0xffff0000, v203
	s_waitcnt lgkmcnt(0)
	v_add_f32_e32 v74, v64, v54
	v_lshlrev_b32_e32 v54, 16, v202
	v_cvt_pk_bf16_f32 v52, v52, v53
	v_cvt_pk_bf16_f32 v53, v62, v63
	v_lshlrev_b32_e32 v62, 16, v204
	v_and_b32_e32 v63, 0xffff0000, v204
	v_lshlrev_b32_e32 v64, 16, v205
	v_and_b32_e32 v65, 0xffff0000, v205
	v_pk_fma_f32 v[48:49], v[48:49], 0.5, v[56:57] op_sel_hi:[1,0,1]
	v_pk_fma_f32 v[46:47], v[46:47], 0.5, v[54:55] op_sel_hi:[1,0,1]
	v_pk_fma_f32 v[54:55], v[44:45], 0.5, v[64:65] op_sel_hi:[1,0,1]
	v_pk_fma_f32 v[44:45], v[42:43], 0.5, v[62:63] op_sel_hi:[1,0,1]
	v_mul_f32_e32 v42, v47, v47
	v_mul_f32_e32 v43, v49, v49
	v_fmac_f32_e32 v42, v46, v46
	v_fmac_f32_e32 v43, v48, v48
	v_add_f32_e32 v42, v42, v43
	v_mul_f32_e32 v43, v45, v45
	v_fmac_f32_e32 v43, v44, v44
	v_add_f32_e32 v42, v43, v42
	v_mul_f32_e32 v43, v55, v55
	v_fmac_f32_e32 v43, v54, v54
	v_add_f32_e32 v62, v43, v42
	v_cvt_pk_bf16_f32 v42, v46, v47
	v_cvt_pk_bf16_f32 v43, v48, v49
	v_lshlrev_b32_e32 v46, 16, v198
	v_and_b32_e32 v47, 0xffff0000, v198
	v_lshlrev_b32_e32 v48, 16, v199
	v_and_b32_e32 v49, 0xffff0000, v199
	v_pk_fma_f32 v[40:41], v[40:41], 0.5, v[48:49] op_sel_hi:[1,0,1]
	v_pk_fma_f32 v[38:39], v[38:39], 0.5, v[46:47] op_sel_hi:[1,0,1]
	v_cvt_pk_bf16_f32 v44, v44, v45
	v_cvt_pk_bf16_f32 v45, v54, v55
	v_lshlrev_b32_e32 v54, 16, v200
	v_and_b32_e32 v55, 0xffff0000, v200
	v_mul_f32_e32 v46, v39, v39
	v_mul_f32_e32 v47, v41, v41
	v_pk_fma_f32 v[34:35], v[34:35], 0.5, v[54:55] op_sel_hi:[1,0,1]
	v_fmac_f32_e32 v46, v38, v38
	v_fmac_f32_e32 v47, v40, v40
	v_lshlrev_b32_e32 v56, 16, v201
	v_and_b32_e32 v57, 0xffff0000, v201
	v_add_f32_e32 v46, v46, v47
	v_mul_f32_e32 v47, v35, v35
	v_pk_fma_f32 v[36:37], v[36:37], 0.5, v[56:57] op_sel_hi:[1,0,1]
	v_fmac_f32_e32 v47, v34, v34
	v_add_f32_e32 v46, v47, v46
	v_mul_f32_e32 v47, v37, v37
	v_fmac_f32_e32 v47, v36, v36
	v_add_f32_e32 v46, v47, v46
	v_add_f32_e32 v46, v46, v62
	v_cvt_pk_bf16_f32 v54, v38, v39
	v_cvt_pk_bf16_f32 v55, v40, v41
	v_cvt_pk_bf16_f32 v56, v34, v35
	ds_bpermute_b32 v34, v145, v46
	v_add_co_u32_e32 v66, vcc, s2, v132
	s_mov_b32 s2, 0xa0000
	s_nop 0
	v_addc_co_u32_e32 v67, vcc, 0, v133, vcc
	v_add_co_u32_e32 v68, vcc, s2, v132
	v_cvt_pk_bf16_f32 v57, v36, v37
	s_waitcnt lgkmcnt(0)
	v_add_f32_e32 v70, v46, v34
	v_addc_co_u32_e32 v69, vcc, 0, v133, vcc
	global_store_dwordx4 v[100:101], v[58:61], off
	global_store_dwordx4 v[100:101], v[50:53], off offset:256
	global_store_dwordx4 v[98:99], v[42:45], off
	global_store_dwordx4 v[98:99], v[54:57], off offset:256
	ds_bpermute_b32 v75, v144, v74
	ds_bpermute_b32 v71, v144, v70
	s_waitcnt vmcnt(12)
	v_lshlrev_b32_e32 v42, 16, v248
	v_and_b32_e32 v43, 0xffff0000, v248
	v_lshlrev_b32_e32 v44, 16, v249
	v_and_b32_e32 v45, 0xffff0000, v249
	v_lshlrev_b32_e32 v50, 16, v250
	v_and_b32_e32 v51, 0xffff0000, v250
	v_lshlrev_b32_e32 v52, 16, v251
	v_and_b32_e32 v53, 0xffff0000, v251
	v_pk_fma_f32 v[32:33], v[32:33], 0.5, v[44:45] op_sel_hi:[1,0,1]
	v_pk_fma_f32 v[30:31], v[30:31], 0.5, v[42:43] op_sel_hi:[1,0,1]
	v_pk_fma_f32 v[42:43], v[28:29], 0.5, v[52:53] op_sel_hi:[1,0,1]
	v_pk_fma_f32 v[28:29], v[26:27], 0.5, v[50:51] op_sel_hi:[1,0,1]
	v_mul_f32_e32 v26, v31, v31
	v_mul_f32_e32 v27, v33, v33
	v_fmac_f32_e32 v26, v30, v30
	v_fmac_f32_e32 v27, v32, v32
	v_add_f32_e32 v26, v26, v27
	v_mul_f32_e32 v27, v29, v29
	v_fmac_f32_e32 v27, v28, v28
	v_add_f32_e32 v26, v27, v26
	v_mul_f32_e32 v27, v43, v43
	v_fmac_f32_e32 v27, v42, v42
	v_add_f32_e32 v50, v27, v26
	v_cvt_pk_bf16_f32 v26, v30, v31
	v_cvt_pk_bf16_f32 v27, v32, v33
	v_lshlrev_b32_e32 v30, 16, v244
	v_and_b32_e32 v31, 0xffff0000, v244
	v_lshlrev_b32_e32 v32, 16, v245
	v_and_b32_e32 v33, 0xffff0000, v245
	v_lshlrev_b32_e32 v44, 16, v247
	v_and_b32_e32 v45, 0xffff0000, v247
	v_pk_fma_f32 v[24:25], v[24:25], 0.5, v[32:33] op_sel_hi:[1,0,1]
	v_pk_fma_f32 v[22:23], v[22:23], 0.5, v[30:31] op_sel_hi:[1,0,1]
	v_cvt_pk_bf16_f32 v28, v28, v29
	v_cvt_pk_bf16_f32 v29, v42, v43
	v_lshlrev_b32_e32 v42, 16, v246
	v_and_b32_e32 v43, 0xffff0000, v246
	v_pk_fma_f32 v[30:31], v[20:21], 0.5, v[44:45] op_sel_hi:[1,0,1]
	v_mul_f32_e32 v20, v23, v23
	v_mul_f32_e32 v21, v25, v25
	v_pk_fma_f32 v[18:19], v[18:19], 0.5, v[42:43] op_sel_hi:[1,0,1]
	v_fmac_f32_e32 v20, v22, v22
	v_fmac_f32_e32 v21, v24, v24
	v_add_f32_e32 v20, v20, v21
	v_mul_f32_e32 v21, v19, v19
	v_fmac_f32_e32 v21, v18, v18
	v_add_f32_e32 v20, v21, v20
	v_mul_f32_e32 v21, v31, v31
	v_fmac_f32_e32 v21, v30, v30
	v_add_f32_e32 v20, v21, v20
	v_add_f32_e32 v32, v20, v50
	v_cvt_pk_bf16_f32 v20, v22, v23
	v_cvt_pk_bf16_f32 v21, v24, v25
	v_cvt_pk_bf16_f32 v22, v18, v19
	ds_bpermute_b32 v18, v145, v32
	v_cvt_pk_bf16_f32 v23, v30, v31
	v_lshlrev_b32_e32 v24, 16, v240
	v_and_b32_e32 v25, 0xffff0000, v240
	v_lshlrev_b32_e32 v30, 16, v241
	v_and_b32_e32 v31, 0xffff0000, v241
	s_waitcnt lgkmcnt(0)
	v_add_f32_e32 v18, v32, v18
	v_lshlrev_b32_e32 v32, 16, v242
	v_and_b32_e32 v33, 0xffff0000, v242
	v_lshlrev_b32_e32 v38, 16, v243
	v_and_b32_e32 v39, 0xffff0000, v243
	v_pk_fma_f32 v[16:17], v[16:17], 0.5, v[30:31] op_sel_hi:[1,0,1]
	v_pk_fma_f32 v[14:15], v[14:15], 0.5, v[24:25] op_sel_hi:[1,0,1]
	v_pk_fma_f32 v[24:25], v[12:13], 0.5, v[38:39] op_sel_hi:[1,0,1]
	v_pk_fma_f32 v[12:13], v[10:11], 0.5, v[32:33] op_sel_hi:[1,0,1]
	v_mul_f32_e32 v10, v15, v15
	v_mul_f32_e32 v11, v17, v17
	v_fmac_f32_e32 v10, v14, v14
	v_fmac_f32_e32 v11, v16, v16
	v_add_f32_e32 v10, v10, v11
	v_mul_f32_e32 v11, v13, v13
	v_fmac_f32_e32 v11, v12, v12
	v_add_f32_e32 v10, v11, v10
	v_mul_f32_e32 v11, v25, v25
	v_fmac_f32_e32 v11, v24, v24
	v_add_f32_e32 v32, v11, v10
	v_cvt_pk_bf16_f32 v10, v14, v15
	v_cvt_pk_bf16_f32 v11, v16, v17
	v_lshlrev_b32_e32 v14, 16, v236
	v_and_b32_e32 v15, 0xffff0000, v236
	v_lshlrev_b32_e32 v16, 16, v237
	v_and_b32_e32 v17, 0xffff0000, v237
	v_lshlrev_b32_e32 v30, 16, v239
	v_and_b32_e32 v31, 0xffff0000, v239
	v_pk_fma_f32 v[8:9], v[8:9], 0.5, v[16:17] op_sel_hi:[1,0,1]
	v_pk_fma_f32 v[6:7], v[6:7], 0.5, v[14:15] op_sel_hi:[1,0,1]
	v_cvt_pk_bf16_f32 v12, v12, v13
	v_cvt_pk_bf16_f32 v13, v24, v25
	v_lshlrev_b32_e32 v24, 16, v238
	v_and_b32_e32 v25, 0xffff0000, v238
	v_pk_fma_f32 v[14:15], v[4:5], 0.5, v[30:31] op_sel_hi:[1,0,1]
	v_mul_f32_e32 v4, v7, v7
	v_mul_f32_e32 v5, v9, v9
	v_pk_fma_f32 v[2:3], v[2:3], 0.5, v[24:25] op_sel_hi:[1,0,1]
	v_fmac_f32_e32 v4, v6, v6
	v_fmac_f32_e32 v5, v8, v8
	v_add_f32_e32 v4, v4, v5
	v_mul_f32_e32 v5, v3, v3
	v_fmac_f32_e32 v5, v2, v2
	v_add_f32_e32 v4, v5, v4
	v_mul_f32_e32 v5, v15, v15
	v_fmac_f32_e32 v5, v14, v14
	v_add_f32_e32 v4, v5, v4
	v_add_f32_e32 v16, v4, v32
	v_cvt_pk_bf16_f32 v4, v6, v7
	v_cvt_pk_bf16_f32 v5, v8, v9
	v_cvt_pk_bf16_f32 v6, v2, v3
	ds_bpermute_b32 v2, v145, v16
	ds_bpermute_b32 v19, v144, v18
	v_cvt_pk_bf16_f32 v7, v14, v15
	global_store_dwordx4 v[68:69], v[26:29], off
	global_store_dwordx4 v[68:69], v[20:23], off offset:256
	global_store_dwordx4 v[66:67], v[10:13], off
	global_store_dwordx4 v[66:67], v[4:7], off offset:256
	s_waitcnt lgkmcnt(1)
	v_add_f32_e32 v2, v16, v2
	ds_bpermute_b32 v3, v144, v2
	s_and_saveexec_b64 s[8:9], s[40:41]
	s_cbranch_execz .LBB0_585
	v_add_f32_e32 v4, v142, v143
	v_fma_f32 v4, v4, s11, 0.5
	v_trunc_f32_e32 v4, v4
	v_mul_f32_e32 v5, 0x2f800000, v4
	v_floor_f32_e32 v5, v5
	v_fmac_f32_e32 v4, 0xcf800000, v5
	v_cvt_u32_f32_e32 v4, v4
	v_cvt_u32_f32_e32 v5, v5
	s_waitcnt lgkmcnt(0)
	v_add_f32_e32 v6, v2, v3
	v_add_f32_e32 v12, v170, v171
	v_lshl_add_u64 v[2:3], s[46:47], 3, v[130:131]
	global_atomic_add_x2 v[2:3], v[4:5], off
	v_fma_f32 v4, v12, s11, 0.5
	v_trunc_f32_e32 v4, v4
	v_mul_f32_e32 v5, 0x2f800000, v4
	v_floor_f32_e32 v5, v5
	v_fmac_f32_e32 v4, 0xcf800000, v5
	v_cvt_u32_f32_e32 v4, v4
	v_cvt_u32_f32_e32 v5, v5
	v_add_f32_e32 v11, v106, v107
	v_add_f32_e32 v10, v102, v103
	v_add_f32_e32 v9, v74, v75
	global_atomic_add_x2 v[2:3], v[4:5], off offset:128
	v_fma_f32 v4, v11, s11, 0.5
	v_trunc_f32_e32 v4, v4
	v_mul_f32_e32 v5, 0x2f800000, v4
	v_floor_f32_e32 v5, v5
	v_fmac_f32_e32 v4, 0xcf800000, v5
	v_cvt_u32_f32_e32 v4, v4
	v_cvt_u32_f32_e32 v5, v5
	v_add_f32_e32 v8, v70, v71
	v_add_f32_e32 v7, v18, v19
	global_atomic_add_x2 v[2:3], v[4:5], off offset:256
	v_fma_f32 v4, v10, s11, 0.5
	v_trunc_f32_e32 v4, v4
	v_mul_f32_e32 v5, 0x2f800000, v4
	v_floor_f32_e32 v5, v5
	v_fmac_f32_e32 v4, 0xcf800000, v5
	v_cvt_u32_f32_e32 v4, v4
	v_cvt_u32_f32_e32 v5, v5
	global_atomic_add_x2 v[2:3], v[4:5], off offset:384
	v_fma_f32 v4, v9, s11, 0.5
	v_trunc_f32_e32 v4, v4
	v_mul_f32_e32 v5, 0x2f800000, v4
	v_floor_f32_e32 v5, v5
	v_fmac_f32_e32 v4, 0xcf800000, v5
	v_cvt_u32_f32_e32 v4, v4
	v_cvt_u32_f32_e32 v5, v5
	global_atomic_add_x2 v[2:3], v[4:5], off offset:1024
	v_fma_f32 v4, v8, s11, 0.5
	v_trunc_f32_e32 v4, v4
	v_mul_f32_e32 v5, 0x2f800000, v4
	v_floor_f32_e32 v5, v5
	v_fmac_f32_e32 v4, 0xcf800000, v5
	v_cvt_u32_f32_e32 v4, v4
	v_cvt_u32_f32_e32 v5, v5
	global_atomic_add_x2 v[2:3], v[4:5], off offset:1152
	v_fma_f32 v4, v7, s11, 0.5
	v_trunc_f32_e32 v4, v4
	v_mul_f32_e32 v5, 0x2f800000, v4
	v_floor_f32_e32 v5, v5
	v_fmac_f32_e32 v4, 0xcf800000, v5
	v_cvt_u32_f32_e32 v4, v4
	v_cvt_u32_f32_e32 v5, v5
	global_atomic_add_x2 v[2:3], v[4:5], off offset:1280
	v_fma_f32 v4, v6, s11, 0.5
	v_trunc_f32_e32 v4, v4
	v_mul_f32_e32 v5, 0x2f800000, v4
	v_floor_f32_e32 v5, v5
	v_fmac_f32_e32 v4, 0xcf800000, v5
	v_cvt_u32_f32_e32 v4, v4
	v_cvt_u32_f32_e32 v5, v5
	global_atomic_add_x2 v[2:3], v[4:5], off offset:1408

.LBB0_1592:
	s_lshl_b32 s8, s12, 8
	s_add_i32 s46, s8, s31
	s_lshl_b32 s2, s2, 8
	s_ashr_i32 s47, s46, 31
	s_or_b32 s8, s2, s33
	s_lshl_b64 s[12:13], s[46:47], 12
	s_add_u32 s2, s34, s12
	s_addc_u32 s12, s35, s13
	s_ashr_i32 s9, s8, 31
	s_lshl_b64 s[8:9], s[8:9], 1
	s_add_u32 s26, s2, s8
	s_addc_u32 s27, s12, s9
	global_load_dwordx4 v[142:145], v146, s[26:27]
	global_load_dwordx4 v[154:157], v146, s[26:27] offset:256
	v_lshl_add_u64 v[132:133], s[26:27], 0, v[146:147]
	v_add_co_u32_e32 v134, vcc, s52, v132
	s_mov_b32 s2, 0x30000
	s_nop 0
	v_addc_co_u32_e32 v135, vcc, 0, v133, vcc
	global_load_dwordx4 v[170:173], v[134:135], off
	global_load_dwordx4 v[174:177], v[134:135], off offset:256
	s_add_u32 s12, s26, 0x30000
	s_addc_u32 s13, s27, 0
	global_load_dwordx4 v[182:185], v146, s[12:13] offset:256
	global_load_dwordx4 v[186:189], v146, s[12:13]
	s_add_u32 s12, s26, s63
	s_addc_u32 s13, s27, 0
	global_load_dwordx4 v[190:193], v146, s[12:13] offset:256
	global_load_dwordx4 v[194:197], v146, s[12:13]
	s_add_u32 s12, s26, 0x90000
	s_addc_u32 s13, s27, 0
	global_load_dwordx4 v[198:201], v146, s[12:13] offset:256
	global_load_dwordx4 v[202:205], v146, s[12:13]
	s_add_u32 s12, s26, 0x80000
	s_addc_u32 s13, s27, 0
	global_load_dwordx4 v[228:231], v146, s[12:13] offset:256
	global_load_dwordx4 v[232:235], v146, s[12:13]
	s_add_u32 s12, s26, 0xb0000
	s_addc_u32 s13, s27, 0
	global_load_dwordx4 v[236:239], v146, s[12:13] offset:256
	global_load_dwordx4 v[240:243], v146, s[12:13]
	s_add_u32 s12, s26, 0xa0000
	s_addc_u32 s13, s27, 0
	global_load_dwordx4 v[244:247], v146, s[12:13] offset:256
	global_load_dwordx4 v[248:251], v146, s[12:13]
	s_waitcnt vmcnt(12)
	v_lshlrev_b32_e32 v178, 16, v142
	v_and_b32_e32 v179, 0xffff0000, v142
	v_lshlrev_b32_e32 v142, 16, v143
	v_and_b32_e32 v143, 0xffff0000, v143
	v_lshlrev_b32_e32 v180, 16, v144
	v_and_b32_e32 v181, 0xffff0000, v144
	v_lshlrev_b32_e32 v144, 16, v145
	v_and_b32_e32 v145, 0xffff0000, v145
	v_pk_add_f32 v[128:129], v[128:129], v[142:143]
	v_pk_add_f32 v[126:127], v[126:127], v[178:179]
	v_pk_add_f32 v[142:143], v[108:109], v[144:145]
	v_pk_add_f32 v[108:109], v[106:107], v[180:181]
	v_mul_f32_e32 v106, v127, v127
	v_mul_f32_e32 v107, v129, v129
	v_fmac_f32_e32 v106, v126, v126
	v_fmac_f32_e32 v107, v128, v128
	v_add_f32_e32 v106, v106, v107
	v_mul_f32_e32 v107, v109, v109
	v_fmac_f32_e32 v107, v108, v108
	v_add_f32_e32 v106, v107, v106
	v_mul_f32_e32 v107, v143, v143
	v_fmac_f32_e32 v107, v142, v142
	v_add_f32_e32 v178, v107, v106
	v_cvt_pk_bf16_f32 v106, v126, v127
	v_cvt_pk_bf16_f32 v107, v128, v129
	v_lshlrev_b32_e32 v126, 16, v154
	v_and_b32_e32 v127, 0xffff0000, v154
	v_lshlrev_b32_e32 v128, 16, v155
	v_and_b32_e32 v129, 0xffff0000, v155
	v_cvt_pk_bf16_f32 v108, v108, v109
	v_cvt_pk_bf16_f32 v109, v142, v143
	v_lshlrev_b32_e32 v142, 16, v156
	v_and_b32_e32 v143, 0xffff0000, v156
	v_lshlrev_b32_e32 v144, 16, v157
	v_and_b32_e32 v145, 0xffff0000, v157
	v_pk_add_f32 v[124:125], v[124:125], v[128:129]
	v_pk_add_f32 v[122:123], v[122:123], v[126:127]
	v_pk_add_f32 v[126:127], v[112:113], v[144:145]
	v_pk_add_f32 v[112:113], v[110:111], v[142:143]
	v_mul_f32_e32 v110, v123, v123
	v_mul_f32_e32 v111, v125, v125
	v_fmac_f32_e32 v110, v122, v122
	v_fmac_f32_e32 v111, v124, v124
	v_add_f32_e32 v110, v110, v111
	v_mul_f32_e32 v111, v113, v113
	v_fmac_f32_e32 v111, v112, v112
	v_add_f32_e32 v110, v111, v110
	v_mul_f32_e32 v111, v127, v127
	v_fmac_f32_e32 v111, v126, v126
	v_add_f32_e32 v110, v111, v110
	v_add_f32_e32 v128, v178, v110
	v_cvt_pk_bf16_f32 v110, v122, v123
	v_and_b32_e32 v123, 64, v222
	v_xor_b32_e32 v122, 16, v222
	v_add_u32_e32 v123, 64, v123
	v_cmp_lt_i32_e32 vcc, v122, v123
	v_cvt_pk_bf16_f32 v111, v124, v125
	v_lshlrev_b32_e32 v124, 16, v171
	v_and_b32_e32 v125, 0xffff0000, v171
	v_cndmask_b32_e32 v122, v222, v122, vcc
	v_lshlrev_b32_e32 v145, 2, v122
	ds_bpermute_b32 v122, v145, v128
	v_cvt_pk_bf16_f32 v112, v112, v113
	v_cvt_pk_bf16_f32 v113, v126, v127
	v_lshlrev_b32_e32 v126, 16, v172
	v_and_b32_e32 v127, 0xffff0000, v172
	s_waitcnt lgkmcnt(0)
	v_add_f32_e32 v142, v128, v122
	v_xor_b32_e32 v122, 32, v222
	v_cmp_lt_i32_e32 vcc, v122, v123
	v_and_b32_e32 v123, 0xffff0000, v170
	v_lshlrev_b32_e32 v128, 16, v173
	v_cndmask_b32_e32 v122, v222, v122, vcc
	v_lshlrev_b32_e32 v144, 2, v122
	v_lshlrev_b32_e32 v122, 16, v170
	v_and_b32_e32 v129, 0xffff0000, v173
	v_pk_add_f32 v[120:121], v[120:121], v[124:125]
	v_pk_add_f32 v[118:119], v[118:119], v[122:123]
	v_pk_add_f32 v[122:123], v[116:117], v[128:129]
	v_pk_add_f32 v[116:117], v[114:115], v[126:127]
	v_mul_f32_e32 v114, v119, v119
	v_mul_f32_e32 v115, v121, v121
	v_fmac_f32_e32 v114, v118, v118
	v_fmac_f32_e32 v115, v120, v120
	v_add_f32_e32 v114, v114, v115
	v_mul_f32_e32 v115, v117, v117
	v_fmac_f32_e32 v115, v116, v116
	v_add_f32_e32 v114, v115, v114
	v_mul_f32_e32 v115, v123, v123
	v_fmac_f32_e32 v115, v122, v122
	v_add_f32_e32 v126, v115, v114
	v_cvt_pk_bf16_f32 v114, v118, v119
	v_cvt_pk_bf16_f32 v115, v120, v121
	v_lshlrev_b32_e32 v118, 16, v174
	v_and_b32_e32 v119, 0xffff0000, v174
	v_lshlrev_b32_e32 v120, 16, v175
	v_and_b32_e32 v121, 0xffff0000, v175
	v_pk_add_f32 v[104:105], v[104:105], v[120:121]
	v_pk_add_f32 v[102:103], v[102:103], v[118:119]
	v_cvt_pk_bf16_f32 v116, v116, v117
	v_cvt_pk_bf16_f32 v117, v122, v123
	v_lshlrev_b32_e32 v122, 16, v176
	v_and_b32_e32 v123, 0xffff0000, v176
	v_mul_f32_e32 v118, v103, v103
	v_mul_f32_e32 v119, v105, v105
	v_pk_add_f32 v[98:99], v[98:99], v[122:123]
	v_fmac_f32_e32 v118, v102, v102
	v_fmac_f32_e32 v119, v104, v104
	v_lshlrev_b32_e32 v124, 16, v177
	v_and_b32_e32 v125, 0xffff0000, v177
	v_add_f32_e32 v118, v118, v119
	v_mul_f32_e32 v119, v99, v99
	v_pk_add_f32 v[100:101], v[100:101], v[124:125]
	v_fmac_f32_e32 v119, v98, v98
	v_add_f32_e32 v118, v119, v118
	v_mul_f32_e32 v119, v101, v101
	v_fmac_f32_e32 v119, v100, v100
	v_add_f32_e32 v118, v119, v118
	v_add_f32_e32 v122, v126, v118
	v_cvt_pk_bf16_f32 v118, v102, v103
	v_cvt_pk_bf16_f32 v119, v104, v105
	v_cvt_pk_bf16_f32 v120, v98, v99
	ds_bpermute_b32 v98, v145, v122
	v_add_co_u32_e32 v126, vcc, s2, v132
	v_cvt_pk_bf16_f32 v121, v100, v101
	s_mov_b32 s2, 0x90000
	s_nop 0
	v_addc_co_u32_e32 v127, vcc, 0, v133, vcc
	v_add_co_u32_e32 v128, vcc, s63, v132
	s_waitcnt lgkmcnt(0)
	v_add_f32_e32 v170, v122, v98
	v_addc_co_u32_e32 v129, vcc, 0, v133, vcc
	global_store_dwordx4 v146, v[106:109], s[26:27]
	global_store_dwordx4 v146, v[110:113], s[26:27] offset:256
	global_store_dwordx4 v[134:135], v[114:117], off
	global_store_dwordx4 v[134:135], v[118:121], off offset:256
	ds_bpermute_b32 v143, v144, v142
	ds_bpermute_b32 v171, v144, v170
	s_waitcnt vmcnt(12)
	v_lshlrev_b32_e32 v106, 16, v194
	v_and_b32_e32 v107, 0xffff0000, v194
	v_lshlrev_b32_e32 v108, 16, v195
	v_and_b32_e32 v109, 0xffff0000, v195
	v_lshlrev_b32_e32 v110, 16, v196
	v_and_b32_e32 v111, 0xffff0000, v196
	v_lshlrev_b32_e32 v112, 16, v197
	v_and_b32_e32 v113, 0xffff0000, v197
	v_pk_add_f32 v[96:97], v[96:97], v[108:109]
	v_pk_add_f32 v[94:95], v[94:95], v[106:107]
	v_pk_add_f32 v[106:107], v[92:93], v[112:113]
	v_pk_add_f32 v[92:93], v[90:91], v[110:111]
	v_mul_f32_e32 v90, v95, v95
	v_mul_f32_e32 v91, v97, v97
	v_fmac_f32_e32 v90, v94, v94
	v_fmac_f32_e32 v91, v96, v96
	v_add_f32_e32 v90, v90, v91
	v_mul_f32_e32 v91, v93, v93
	v_fmac_f32_e32 v91, v92, v92
	v_add_f32_e32 v90, v91, v90
	v_mul_f32_e32 v91, v107, v107
	v_fmac_f32_e32 v91, v106, v106
	v_add_f32_e32 v110, v91, v90
	v_cvt_pk_bf16_f32 v90, v94, v95
	v_cvt_pk_bf16_f32 v91, v96, v97
	v_lshlrev_b32_e32 v94, 16, v190
	v_and_b32_e32 v95, 0xffff0000, v190
	v_lshlrev_b32_e32 v96, 16, v191
	v_and_b32_e32 v97, 0xffff0000, v191
	v_cvt_pk_bf16_f32 v92, v92, v93
	v_cvt_pk_bf16_f32 v93, v106, v107
	v_lshlrev_b32_e32 v106, 16, v192
	v_and_b32_e32 v107, 0xffff0000, v192
	v_lshlrev_b32_e32 v108, 16, v193
	v_and_b32_e32 v109, 0xffff0000, v193
	v_pk_add_f32 v[88:89], v[88:89], v[96:97]
	v_pk_add_f32 v[86:87], v[86:87], v[94:95]
	v_pk_add_f32 v[94:95], v[84:85], v[108:109]
	v_pk_add_f32 v[84:85], v[82:83], v[106:107]
	v_mul_f32_e32 v82, v87, v87
	v_mul_f32_e32 v83, v89, v89
	v_fmac_f32_e32 v82, v86, v86
	v_fmac_f32_e32 v83, v88, v88
	v_add_f32_e32 v82, v82, v83
	v_mul_f32_e32 v83, v85, v85
	v_fmac_f32_e32 v83, v84, v84
	v_add_f32_e32 v82, v83, v82
	v_mul_f32_e32 v83, v95, v95
	v_fmac_f32_e32 v83, v94, v94
	v_add_f32_e32 v82, v83, v82
	v_add_f32_e32 v96, v82, v110
	v_cvt_pk_bf16_f32 v82, v86, v87
	ds_bpermute_b32 v86, v145, v96
	v_cvt_pk_bf16_f32 v83, v88, v89
	v_and_b32_e32 v87, 0xffff0000, v186
	v_lshlrev_b32_e32 v88, 16, v187
	v_and_b32_e32 v89, 0xffff0000, v187
	s_waitcnt lgkmcnt(0)
	v_add_f32_e32 v106, v96, v86
	v_lshlrev_b32_e32 v86, 16, v186
	v_cvt_pk_bf16_f32 v84, v84, v85
	v_cvt_pk_bf16_f32 v85, v94, v95
	v_lshlrev_b32_e32 v94, 16, v188
	v_and_b32_e32 v95, 0xffff0000, v188
	v_lshlrev_b32_e32 v96, 16, v189
	v_and_b32_e32 v97, 0xffff0000, v189
	v_pk_add_f32 v[80:81], v[80:81], v[88:89]
	v_pk_add_f32 v[78:79], v[78:79], v[86:87]
	v_pk_add_f32 v[86:87], v[76:77], v[96:97]
	v_pk_add_f32 v[76:77], v[74:75], v[94:95]
	v_mul_f32_e32 v74, v79, v79
	v_mul_f32_e32 v75, v81, v81
	v_fmac_f32_e32 v74, v78, v78
	v_fmac_f32_e32 v75, v80, v80
	v_add_f32_e32 v74, v74, v75
	v_mul_f32_e32 v75, v77, v77
	v_fmac_f32_e32 v75, v76, v76
	v_add_f32_e32 v74, v75, v74
	v_mul_f32_e32 v75, v87, v87
	v_fmac_f32_e32 v75, v86, v86
	v_add_f32_e32 v94, v75, v74
	v_cvt_pk_bf16_f32 v74, v78, v79
	v_cvt_pk_bf16_f32 v75, v80, v81
	v_lshlrev_b32_e32 v78, 16, v182
	v_and_b32_e32 v79, 0xffff0000, v182
	v_lshlrev_b32_e32 v80, 16, v183
	v_and_b32_e32 v81, 0xffff0000, v183
	v_pk_add_f32 v[72:73], v[72:73], v[80:81]
	v_pk_add_f32 v[70:71], v[70:71], v[78:79]
	v_cvt_pk_bf16_f32 v76, v76, v77
	v_cvt_pk_bf16_f32 v77, v86, v87
	v_lshlrev_b32_e32 v86, 16, v184
	v_and_b32_e32 v87, 0xffff0000, v184
	v_mul_f32_e32 v78, v71, v71
	v_mul_f32_e32 v79, v73, v73
	v_pk_add_f32 v[66:67], v[66:67], v[86:87]
	v_fmac_f32_e32 v78, v70, v70
	v_fmac_f32_e32 v79, v72, v72
	v_lshlrev_b32_e32 v88, 16, v185
	v_and_b32_e32 v89, 0xffff0000, v185
	v_add_f32_e32 v78, v78, v79
	v_mul_f32_e32 v79, v67, v67
	v_pk_add_f32 v[68:69], v[68:69], v[88:89]
	v_fmac_f32_e32 v79, v66, v66
	v_add_f32_e32 v78, v79, v78
	v_mul_f32_e32 v79, v69, v69
	v_fmac_f32_e32 v79, v68, v68
	v_add_f32_e32 v78, v79, v78
	v_add_f32_e32 v78, v78, v94
	v_cvt_pk_bf16_f32 v86, v70, v71
	v_cvt_pk_bf16_f32 v87, v72, v73
	v_cvt_pk_bf16_f32 v88, v66, v67
	ds_bpermute_b32 v66, v145, v78
	v_add_co_u32_e32 v98, vcc, s2, v132
	s_mov_b32 s2, 0x80000
	s_nop 0
	v_addc_co_u32_e32 v99, vcc, 0, v133, vcc
	v_add_co_u32_e32 v100, vcc, s2, v132
	v_cvt_pk_bf16_f32 v89, v68, v69
	s_waitcnt lgkmcnt(0)
	v_add_f32_e32 v102, v78, v66
	v_addc_co_u32_e32 v101, vcc, 0, v133, vcc
	global_store_dwordx4 v[128:129], v[90:93], off
	global_store_dwordx4 v[128:129], v[82:85], off offset:256
	global_store_dwordx4 v[126:127], v[74:77], off
	global_store_dwordx4 v[126:127], v[86:89], off offset:256
	s_mov_b32 s2, 0xb0000
	ds_bpermute_b32 v107, v144, v106
	ds_bpermute_b32 v103, v144, v102
	s_waitcnt vmcnt(12)
	v_lshlrev_b32_e32 v74, 16, v232
	v_and_b32_e32 v75, 0xffff0000, v232
	v_lshlrev_b32_e32 v76, 16, v233
	v_and_b32_e32 v77, 0xffff0000, v233
	v_lshlrev_b32_e32 v82, 16, v234
	v_and_b32_e32 v83, 0xffff0000, v234
	v_lshlrev_b32_e32 v84, 16, v235
	v_and_b32_e32 v85, 0xffff0000, v235
	v_pk_add_f32 v[64:65], v[64:65], v[76:77]
	v_pk_add_f32 v[62:63], v[62:63], v[74:75]
	v_pk_add_f32 v[74:75], v[60:61], v[84:85]
	v_pk_add_f32 v[60:61], v[58:59], v[82:83]
	v_mul_f32_e32 v58, v63, v63
	v_mul_f32_e32 v59, v65, v65
	v_fmac_f32_e32 v58, v62, v62
	v_fmac_f32_e32 v59, v64, v64
	v_add_f32_e32 v58, v58, v59
	v_mul_f32_e32 v59, v61, v61
	v_fmac_f32_e32 v59, v60, v60
	v_add_f32_e32 v58, v59, v58
	v_mul_f32_e32 v59, v75, v75
	v_fmac_f32_e32 v59, v74, v74
	v_add_f32_e32 v82, v59, v58
	v_cvt_pk_bf16_f32 v58, v62, v63
	v_cvt_pk_bf16_f32 v59, v64, v65
	v_lshlrev_b32_e32 v62, 16, v228
	v_and_b32_e32 v63, 0xffff0000, v228
	v_lshlrev_b32_e32 v64, 16, v229
	v_and_b32_e32 v65, 0xffff0000, v229
	v_cvt_pk_bf16_f32 v60, v60, v61
	v_cvt_pk_bf16_f32 v61, v74, v75
	v_lshlrev_b32_e32 v74, 16, v230
	v_and_b32_e32 v75, 0xffff0000, v230
	v_lshlrev_b32_e32 v76, 16, v231
	v_and_b32_e32 v77, 0xffff0000, v231
	v_pk_add_f32 v[56:57], v[56:57], v[64:65]
	v_pk_add_f32 v[54:55], v[54:55], v[62:63]
	v_pk_add_f32 v[62:63], v[52:53], v[76:77]
	v_pk_add_f32 v[52:53], v[50:51], v[74:75]
	v_mul_f32_e32 v50, v55, v55
	v_mul_f32_e32 v51, v57, v57
	v_fmac_f32_e32 v50, v54, v54
	v_fmac_f32_e32 v51, v56, v56
	v_add_f32_e32 v50, v50, v51
	v_mul_f32_e32 v51, v53, v53
	v_fmac_f32_e32 v51, v52, v52
	v_add_f32_e32 v50, v51, v50
	v_mul_f32_e32 v51, v63, v63
	v_fmac_f32_e32 v51, v62, v62
	v_add_f32_e32 v50, v51, v50
	v_add_f32_e32 v64, v50, v82
	v_cvt_pk_bf16_f32 v50, v54, v55
	ds_bpermute_b32 v54, v145, v64
	v_cvt_pk_bf16_f32 v51, v56, v57
	v_and_b32_e32 v55, 0xffff0000, v202
	v_lshlrev_b32_e32 v56, 16, v203
	v_and_b32_e32 v57, 0xffff0000, v203
	s_waitcnt lgkmcnt(0)
	v_add_f32_e32 v74, v64, v54
	v_lshlrev_b32_e32 v54, 16, v202
	v_cvt_pk_bf16_f32 v52, v52, v53
	v_cvt_pk_bf16_f32 v53, v62, v63
	v_lshlrev_b32_e32 v62, 16, v204
	v_and_b32_e32 v63, 0xffff0000, v204
	v_lshlrev_b32_e32 v64, 16, v205
	v_and_b32_e32 v65, 0xffff0000, v205
	v_pk_add_f32 v[48:49], v[48:49], v[56:57]
	v_pk_add_f32 v[46:47], v[46:47], v[54:55]
	v_pk_add_f32 v[54:55], v[44:45], v[64:65]
	v_pk_add_f32 v[44:45], v[42:43], v[62:63]
	v_mul_f32_e32 v42, v47, v47
	v_mul_f32_e32 v43, v49, v49
	v_fmac_f32_e32 v42, v46, v46
	v_fmac_f32_e32 v43, v48, v48
	v_add_f32_e32 v42, v42, v43
	v_mul_f32_e32 v43, v45, v45
	v_fmac_f32_e32 v43, v44, v44
	v_add_f32_e32 v42, v43, v42
	v_mul_f32_e32 v43, v55, v55
	v_fmac_f32_e32 v43, v54, v54
	v_add_f32_e32 v62, v43, v42
	v_cvt_pk_bf16_f32 v42, v46, v47
	v_cvt_pk_bf16_f32 v43, v48, v49
	v_lshlrev_b32_e32 v46, 16, v198
	v_and_b32_e32 v47, 0xffff0000, v198
	v_lshlrev_b32_e32 v48, 16, v199
	v_and_b32_e32 v49, 0xffff0000, v199
	v_pk_add_f32 v[40:41], v[40:41], v[48:49]
	v_pk_add_f32 v[38:39], v[38:39], v[46:47]
	v_cvt_pk_bf16_f32 v44, v44, v45
	v_cvt_pk_bf16_f32 v45, v54, v55
	v_lshlrev_b32_e32 v54, 16, v200
	v_and_b32_e32 v55, 0xffff0000, v200
	v_mul_f32_e32 v46, v39, v39
	v_mul_f32_e32 v47, v41, v41
	v_pk_add_f32 v[34:35], v[34:35], v[54:55]
	v_fmac_f32_e32 v46, v38, v38
	v_fmac_f32_e32 v47, v40, v40
	v_lshlrev_b32_e32 v56, 16, v201
	v_and_b32_e32 v57, 0xffff0000, v201
	v_add_f32_e32 v46, v46, v47
	v_mul_f32_e32 v47, v35, v35
	v_pk_add_f32 v[36:37], v[36:37], v[56:57]
	v_fmac_f32_e32 v47, v34, v34
	v_add_f32_e32 v46, v47, v46
	v_mul_f32_e32 v47, v37, v37
	v_fmac_f32_e32 v47, v36, v36
	v_add_f32_e32 v46, v47, v46
	v_add_f32_e32 v46, v46, v62
	v_cvt_pk_bf16_f32 v54, v38, v39
	v_cvt_pk_bf16_f32 v55, v40, v41
	v_cvt_pk_bf16_f32 v56, v34, v35
	ds_bpermute_b32 v34, v145, v46
	v_add_co_u32_e32 v66, vcc, s2, v132
	s_mov_b32 s2, 0xa0000
	s_nop 0
	v_addc_co_u32_e32 v67, vcc, 0, v133, vcc
	v_add_co_u32_e32 v68, vcc, s2, v132
	v_cvt_pk_bf16_f32 v57, v36, v37
	s_waitcnt lgkmcnt(0)
	v_add_f32_e32 v70, v46, v34
	v_addc_co_u32_e32 v69, vcc, 0, v133, vcc
	global_store_dwordx4 v[100:101], v[58:61], off
	global_store_dwordx4 v[100:101], v[50:53], off offset:256
	global_store_dwordx4 v[98:99], v[42:45], off
	global_store_dwordx4 v[98:99], v[54:57], off offset:256
	ds_bpermute_b32 v75, v144, v74
	ds_bpermute_b32 v71, v144, v70
	s_waitcnt vmcnt(12)
	v_lshlrev_b32_e32 v42, 16, v248
	v_and_b32_e32 v43, 0xffff0000, v248
	v_lshlrev_b32_e32 v44, 16, v249
	v_and_b32_e32 v45, 0xffff0000, v249
	v_lshlrev_b32_e32 v50, 16, v250
	v_and_b32_e32 v51, 0xffff0000, v250
	v_lshlrev_b32_e32 v52, 16, v251
	v_and_b32_e32 v53, 0xffff0000, v251
	v_pk_add_f32 v[32:33], v[32:33], v[44:45]
	v_pk_add_f32 v[30:31], v[30:31], v[42:43]
	v_pk_add_f32 v[42:43], v[28:29], v[52:53]
	v_pk_add_f32 v[28:29], v[26:27], v[50:51]
	v_mul_f32_e32 v26, v31, v31
	v_mul_f32_e32 v27, v33, v33
	v_fmac_f32_e32 v26, v30, v30
	v_fmac_f32_e32 v27, v32, v32
	v_add_f32_e32 v26, v26, v27
	v_mul_f32_e32 v27, v29, v29
	v_fmac_f32_e32 v27, v28, v28
	v_add_f32_e32 v26, v27, v26
	v_mul_f32_e32 v27, v43, v43
	v_fmac_f32_e32 v27, v42, v42
	v_add_f32_e32 v50, v27, v26
	v_cvt_pk_bf16_f32 v26, v30, v31
	v_cvt_pk_bf16_f32 v27, v32, v33
	v_lshlrev_b32_e32 v30, 16, v244
	v_and_b32_e32 v31, 0xffff0000, v244
	v_lshlrev_b32_e32 v32, 16, v245
	v_and_b32_e32 v33, 0xffff0000, v245
	v_lshlrev_b32_e32 v44, 16, v247
	v_and_b32_e32 v45, 0xffff0000, v247
	v_pk_add_f32 v[24:25], v[24:25], v[32:33]
	v_pk_add_f32 v[22:23], v[22:23], v[30:31]
	v_cvt_pk_bf16_f32 v28, v28, v29
	v_cvt_pk_bf16_f32 v29, v42, v43
	v_lshlrev_b32_e32 v42, 16, v246
	v_and_b32_e32 v43, 0xffff0000, v246
	v_pk_add_f32 v[30:31], v[20:21], v[44:45]
	v_mul_f32_e32 v20, v23, v23
	v_mul_f32_e32 v21, v25, v25
	v_pk_add_f32 v[18:19], v[18:19], v[42:43]
	v_fmac_f32_e32 v20, v22, v22
	v_fmac_f32_e32 v21, v24, v24
	v_add_f32_e32 v20, v20, v21
	v_mul_f32_e32 v21, v19, v19
	v_fmac_f32_e32 v21, v18, v18
	v_add_f32_e32 v20, v21, v20
	v_mul_f32_e32 v21, v31, v31
	v_fmac_f32_e32 v21, v30, v30
	v_add_f32_e32 v20, v21, v20
	v_add_f32_e32 v32, v20, v50
	v_cvt_pk_bf16_f32 v20, v22, v23
	v_cvt_pk_bf16_f32 v21, v24, v25
	v_cvt_pk_bf16_f32 v22, v18, v19
	ds_bpermute_b32 v18, v145, v32
	v_cvt_pk_bf16_f32 v23, v30, v31
	v_lshlrev_b32_e32 v24, 16, v240
	v_and_b32_e32 v25, 0xffff0000, v240
	v_lshlrev_b32_e32 v30, 16, v241
	v_and_b32_e32 v31, 0xffff0000, v241
	s_waitcnt lgkmcnt(0)
	v_add_f32_e32 v18, v32, v18
	v_lshlrev_b32_e32 v32, 16, v242
	v_and_b32_e32 v33, 0xffff0000, v242
	v_lshlrev_b32_e32 v38, 16, v243
	v_and_b32_e32 v39, 0xffff0000, v243
	v_pk_add_f32 v[16:17], v[16:17], v[30:31]
	v_pk_add_f32 v[14:15], v[14:15], v[24:25]
	v_pk_add_f32 v[24:25], v[12:13], v[38:39]
	v_pk_add_f32 v[12:13], v[10:11], v[32:33]
	v_mul_f32_e32 v10, v15, v15
	v_mul_f32_e32 v11, v17, v17
	v_fmac_f32_e32 v10, v14, v14
	v_fmac_f32_e32 v11, v16, v16
	v_add_f32_e32 v10, v10, v11
	v_mul_f32_e32 v11, v13, v13
	v_fmac_f32_e32 v11, v12, v12
	v_add_f32_e32 v10, v11, v10
	v_mul_f32_e32 v11, v25, v25
	v_fmac_f32_e32 v11, v24, v24
	v_add_f32_e32 v32, v11, v10
	v_cvt_pk_bf16_f32 v10, v14, v15
	v_cvt_pk_bf16_f32 v11, v16, v17
	v_lshlrev_b32_e32 v14, 16, v236
	v_and_b32_e32 v15, 0xffff0000, v236
	v_lshlrev_b32_e32 v16, 16, v237
	v_and_b32_e32 v17, 0xffff0000, v237
	v_lshlrev_b32_e32 v30, 16, v239
	v_and_b32_e32 v31, 0xffff0000, v239
	v_pk_add_f32 v[8:9], v[8:9], v[16:17]
	v_pk_add_f32 v[6:7], v[6:7], v[14:15]
	v_cvt_pk_bf16_f32 v12, v12, v13
	v_cvt_pk_bf16_f32 v13, v24, v25
	v_lshlrev_b32_e32 v24, 16, v238
	v_and_b32_e32 v25, 0xffff0000, v238
	v_pk_add_f32 v[14:15], v[4:5], v[30:31]
	v_mul_f32_e32 v4, v7, v7
	v_mul_f32_e32 v5, v9, v9
	v_pk_add_f32 v[2:3], v[2:3], v[24:25]
	v_fmac_f32_e32 v4, v6, v6
	v_fmac_f32_e32 v5, v8, v8
	v_add_f32_e32 v4, v4, v5
	v_mul_f32_e32 v5, v3, v3
	v_fmac_f32_e32 v5, v2, v2
	v_add_f32_e32 v4, v5, v4
	v_mul_f32_e32 v5, v15, v15
	v_fmac_f32_e32 v5, v14, v14
	v_add_f32_e32 v4, v5, v4
	v_add_f32_e32 v16, v4, v32
	v_cvt_pk_bf16_f32 v4, v6, v7
	v_cvt_pk_bf16_f32 v5, v8, v9
	v_cvt_pk_bf16_f32 v6, v2, v3
	ds_bpermute_b32 v2, v145, v16
	ds_bpermute_b32 v19, v144, v18
	v_cvt_pk_bf16_f32 v7, v14, v15
	global_store_dwordx4 v[68:69], v[26:29], off
	global_store_dwordx4 v[68:69], v[20:23], off offset:256
	global_store_dwordx4 v[66:67], v[10:13], off
	global_store_dwordx4 v[66:67], v[4:7], off offset:256
	s_waitcnt lgkmcnt(1)
	v_add_f32_e32 v2, v16, v2
	ds_bpermute_b32 v3, v144, v2
	s_and_saveexec_b64 s[8:9], s[40:41]
	s_cbranch_execz .LBB0_1594
	v_add_f32_e32 v4, v142, v143
	v_fma_f32 v4, v4, s11, 0.5
	v_trunc_f32_e32 v4, v4
	v_mul_f32_e32 v5, 0x2f800000, v4
	v_floor_f32_e32 v5, v5
	v_fmac_f32_e32 v4, 0xcf800000, v5
	v_cvt_u32_f32_e32 v4, v4
	v_cvt_u32_f32_e32 v5, v5
	s_waitcnt lgkmcnt(0)
	v_add_f32_e32 v6, v2, v3
	v_add_f32_e32 v12, v170, v171
	v_lshl_add_u64 v[2:3], s[46:47], 3, v[130:131]
	global_atomic_add_x2 v[2:3], v[4:5], off
	v_fma_f32 v4, v12, s11, 0.5
	v_trunc_f32_e32 v4, v4
	v_mul_f32_e32 v5, 0x2f800000, v4
	v_floor_f32_e32 v5, v5
	v_fmac_f32_e32 v4, 0xcf800000, v5
	v_cvt_u32_f32_e32 v4, v4
	v_cvt_u32_f32_e32 v5, v5
	v_add_f32_e32 v11, v106, v107
	v_add_f32_e32 v10, v102, v103
	v_add_f32_e32 v9, v74, v75
	global_atomic_add_x2 v[2:3], v[4:5], off offset:128
	v_fma_f32 v4, v11, s11, 0.5
	v_trunc_f32_e32 v4, v4
	v_mul_f32_e32 v5, 0x2f800000, v4
	v_floor_f32_e32 v5, v5
	v_fmac_f32_e32 v4, 0xcf800000, v5
	v_cvt_u32_f32_e32 v4, v4
	v_cvt_u32_f32_e32 v5, v5
	v_add_f32_e32 v8, v70, v71
	v_add_f32_e32 v7, v18, v19
	global_atomic_add_x2 v[2:3], v[4:5], off offset:256
	v_fma_f32 v4, v10, s11, 0.5
	v_trunc_f32_e32 v4, v4
	v_mul_f32_e32 v5, 0x2f800000, v4
	v_floor_f32_e32 v5, v5
	v_fmac_f32_e32 v4, 0xcf800000, v5
	v_cvt_u32_f32_e32 v4, v4
	v_cvt_u32_f32_e32 v5, v5
	global_atomic_add_x2 v[2:3], v[4:5], off offset:384
	v_fma_f32 v4, v9, s11, 0.5
	v_trunc_f32_e32 v4, v4
	v_mul_f32_e32 v5, 0x2f800000, v4
	v_floor_f32_e32 v5, v5
	v_fmac_f32_e32 v4, 0xcf800000, v5
	v_cvt_u32_f32_e32 v4, v4
	v_cvt_u32_f32_e32 v5, v5
	global_atomic_add_x2 v[2:3], v[4:5], off offset:1024
	v_fma_f32 v4, v8, s11, 0.5
	v_trunc_f32_e32 v4, v4
	v_mul_f32_e32 v5, 0x2f800000, v4
	v_floor_f32_e32 v5, v5
	v_fmac_f32_e32 v4, 0xcf800000, v5
	v_cvt_u32_f32_e32 v4, v4
	v_cvt_u32_f32_e32 v5, v5
	global_atomic_add_x2 v[2:3], v[4:5], off offset:1152
	v_fma_f32 v4, v7, s11, 0.5
	v_trunc_f32_e32 v4, v4
	v_mul_f32_e32 v5, 0x2f800000, v4
	v_floor_f32_e32 v5, v5
	v_fmac_f32_e32 v4, 0xcf800000, v5
	v_cvt_u32_f32_e32 v4, v4
	v_cvt_u32_f32_e32 v5, v5
	global_atomic_add_x2 v[2:3], v[4:5], off offset:1280
	v_fma_f32 v4, v6, s11, 0.5
	v_trunc_f32_e32 v4, v4
	v_mul_f32_e32 v5, 0x2f800000, v4
	v_floor_f32_e32 v5, v5
	v_fmac_f32_e32 v4, 0xcf800000, v5
	v_cvt_u32_f32_e32 v4, v4
	v_cvt_u32_f32_e32 v5, v5
	global_atomic_add_x2 v[2:3], v[4:5], off offset:1408

.LBB0_2159:
	s_lshl_b32 s8, s12, 8
	s_add_i32 s46, s8, s34
	s_lshl_b32 s2, s2, 8
	s_ashr_i32 s47, s46, 31
	s_or_b32 s8, s2, s35
	s_lshl_b64 s[12:13], s[46:47], 12
	s_add_u32 s2, s36, s12
	s_addc_u32 s12, s37, s13
	s_ashr_i32 s9, s8, 31
	s_lshl_b64 s[8:9], s[8:9], 1
	s_add_u32 s26, s2, s8
	s_addc_u32 s27, s12, s9
	global_load_dwordx4 v[142:145], v146, s[26:27]
	global_load_dwordx4 v[154:157], v146, s[26:27] offset:256
	v_lshl_add_u64 v[132:133], s[26:27], 0, v[146:147]
	s_mov_b32 s2, 0x10000
	v_add_co_u32_e32 v134, vcc, s2, v132
	s_mov_b32 s2, 0x30000
	s_nop 0
	v_addc_co_u32_e32 v135, vcc, 0, v133, vcc
	global_load_dwordx4 v[170:173], v[134:135], off
	global_load_dwordx4 v[174:177], v[134:135], off offset:256
	s_add_u32 s12, s26, 0x30000
	s_addc_u32 s13, s27, 0
	global_load_dwordx4 v[182:185], v146, s[12:13] offset:256
	global_load_dwordx4 v[186:189], v146, s[12:13]
	s_add_u32 s12, s26, s63
	s_addc_u32 s13, s27, 0
	global_load_dwordx4 v[190:193], v146, s[12:13] offset:256
	global_load_dwordx4 v[194:197], v146, s[12:13]
	s_add_u32 s12, s26, 0x90000
	s_addc_u32 s13, s27, 0
	global_load_dwordx4 v[198:201], v146, s[12:13] offset:256
	global_load_dwordx4 v[202:205], v146, s[12:13]
	s_add_u32 s12, s26, 0x80000
	s_addc_u32 s13, s27, 0
	global_load_dwordx4 v[228:231], v146, s[12:13] offset:256
	global_load_dwordx4 v[232:235], v146, s[12:13]
	s_add_u32 s12, s26, 0xb0000
	s_addc_u32 s13, s27, 0
	global_load_dwordx4 v[236:239], v146, s[12:13] offset:256
	global_load_dwordx4 v[240:243], v146, s[12:13]
	s_add_u32 s12, s26, 0xa0000
	s_addc_u32 s13, s27, 0
	global_load_dwordx4 v[244:247], v146, s[12:13] offset:256
	global_load_dwordx4 v[248:251], v146, s[12:13]
	s_waitcnt vmcnt(12)
	v_lshlrev_b32_e32 v178, 16, v142
	v_and_b32_e32 v179, 0xffff0000, v142
	v_lshlrev_b32_e32 v142, 16, v143
	v_and_b32_e32 v143, 0xffff0000, v143
	v_lshlrev_b32_e32 v180, 16, v144
	v_and_b32_e32 v181, 0xffff0000, v144
	v_lshlrev_b32_e32 v144, 16, v145
	v_and_b32_e32 v145, 0xffff0000, v145
	v_pk_fma_f32 v[128:129], v[128:129], 0.5, v[142:143] op_sel_hi:[1,0,1]
	v_pk_fma_f32 v[126:127], v[126:127], 0.5, v[178:179] op_sel_hi:[1,0,1]
	v_pk_fma_f32 v[142:143], v[108:109], 0.5, v[144:145] op_sel_hi:[1,0,1]
	v_pk_fma_f32 v[108:109], v[106:107], 0.5, v[180:181] op_sel_hi:[1,0,1]
	v_mul_f32_e32 v106, v127, v127
	v_mul_f32_e32 v107, v129, v129
	v_fmac_f32_e32 v106, v126, v126
	v_fmac_f32_e32 v107, v128, v128
	v_add_f32_e32 v106, v106, v107
	v_mul_f32_e32 v107, v109, v109
	v_fmac_f32_e32 v107, v108, v108
	v_add_f32_e32 v106, v107, v106
	v_mul_f32_e32 v107, v143, v143
	v_fmac_f32_e32 v107, v142, v142
	v_add_f32_e32 v178, v107, v106
	v_cvt_pk_bf16_f32 v106, v126, v127
	v_cvt_pk_bf16_f32 v107, v128, v129
	v_lshlrev_b32_e32 v126, 16, v154
	v_and_b32_e32 v127, 0xffff0000, v154
	v_lshlrev_b32_e32 v128, 16, v155
	v_and_b32_e32 v129, 0xffff0000, v155
	v_cvt_pk_bf16_f32 v108, v108, v109
	v_cvt_pk_bf16_f32 v109, v142, v143
	v_lshlrev_b32_e32 v142, 16, v156
	v_and_b32_e32 v143, 0xffff0000, v156
	v_lshlrev_b32_e32 v144, 16, v157
	v_and_b32_e32 v145, 0xffff0000, v157
	v_pk_fma_f32 v[124:125], v[124:125], 0.5, v[128:129] op_sel_hi:[1,0,1]
	v_pk_fma_f32 v[122:123], v[122:123], 0.5, v[126:127] op_sel_hi:[1,0,1]
	v_pk_fma_f32 v[126:127], v[112:113], 0.5, v[144:145] op_sel_hi:[1,0,1]
	v_pk_fma_f32 v[112:113], v[110:111], 0.5, v[142:143] op_sel_hi:[1,0,1]
	v_mul_f32_e32 v110, v123, v123
	v_mul_f32_e32 v111, v125, v125
	v_fmac_f32_e32 v110, v122, v122
	v_fmac_f32_e32 v111, v124, v124
	v_add_f32_e32 v110, v110, v111
	v_mul_f32_e32 v111, v113, v113
	v_fmac_f32_e32 v111, v112, v112
	v_add_f32_e32 v110, v111, v110
	v_mul_f32_e32 v111, v127, v127
	v_fmac_f32_e32 v111, v126, v126
	v_add_f32_e32 v110, v111, v110
	v_add_f32_e32 v128, v178, v110
	v_cvt_pk_bf16_f32 v110, v122, v123
	v_and_b32_e32 v123, 64, v222
	v_xor_b32_e32 v122, 16, v222
	v_add_u32_e32 v123, 64, v123
	v_cmp_lt_i32_e32 vcc, v122, v123
	v_cvt_pk_bf16_f32 v111, v124, v125
	v_lshlrev_b32_e32 v124, 16, v171
	v_and_b32_e32 v125, 0xffff0000, v171
	v_cndmask_b32_e32 v122, v222, v122, vcc
	v_lshlrev_b32_e32 v145, 2, v122
	ds_bpermute_b32 v122, v145, v128
	v_cvt_pk_bf16_f32 v112, v112, v113
	v_cvt_pk_bf16_f32 v113, v126, v127
	v_lshlrev_b32_e32 v126, 16, v172
	v_and_b32_e32 v127, 0xffff0000, v172
	s_waitcnt lgkmcnt(0)
	v_add_f32_e32 v142, v128, v122
	v_xor_b32_e32 v122, 32, v222
	v_cmp_lt_i32_e32 vcc, v122, v123
	v_and_b32_e32 v123, 0xffff0000, v170
	v_lshlrev_b32_e32 v128, 16, v173
	v_cndmask_b32_e32 v122, v222, v122, vcc
	v_lshlrev_b32_e32 v144, 2, v122
	v_lshlrev_b32_e32 v122, 16, v170
	v_and_b32_e32 v129, 0xffff0000, v173
	v_pk_fma_f32 v[120:121], v[120:121], 0.5, v[124:125] op_sel_hi:[1,0,1]
	v_pk_fma_f32 v[118:119], v[118:119], 0.5, v[122:123] op_sel_hi:[1,0,1]
	v_pk_fma_f32 v[122:123], v[116:117], 0.5, v[128:129] op_sel_hi:[1,0,1]
	v_pk_fma_f32 v[116:117], v[114:115], 0.5, v[126:127] op_sel_hi:[1,0,1]
	v_mul_f32_e32 v114, v119, v119
	v_mul_f32_e32 v115, v121, v121
	v_fmac_f32_e32 v114, v118, v118
	v_fmac_f32_e32 v115, v120, v120
	v_add_f32_e32 v114, v114, v115
	v_mul_f32_e32 v115, v117, v117
	v_fmac_f32_e32 v115, v116, v116
	v_add_f32_e32 v114, v115, v114
	v_mul_f32_e32 v115, v123, v123
	v_fmac_f32_e32 v115, v122, v122
	v_add_f32_e32 v126, v115, v114
	v_cvt_pk_bf16_f32 v114, v118, v119
	v_cvt_pk_bf16_f32 v115, v120, v121
	v_lshlrev_b32_e32 v118, 16, v174
	v_and_b32_e32 v119, 0xffff0000, v174
	v_lshlrev_b32_e32 v120, 16, v175
	v_and_b32_e32 v121, 0xffff0000, v175
	v_pk_fma_f32 v[104:105], v[104:105], 0.5, v[120:121] op_sel_hi:[1,0,1]
	v_pk_fma_f32 v[102:103], v[102:103], 0.5, v[118:119] op_sel_hi:[1,0,1]
	v_cvt_pk_bf16_f32 v116, v116, v117
	v_cvt_pk_bf16_f32 v117, v122, v123
	v_lshlrev_b32_e32 v122, 16, v176
	v_and_b32_e32 v123, 0xffff0000, v176
	v_mul_f32_e32 v118, v103, v103
	v_mul_f32_e32 v119, v105, v105
	v_pk_fma_f32 v[98:99], v[98:99], 0.5, v[122:123] op_sel_hi:[1,0,1]
	v_fmac_f32_e32 v118, v102, v102
	v_fmac_f32_e32 v119, v104, v104
	v_lshlrev_b32_e32 v124, 16, v177
	v_and_b32_e32 v125, 0xffff0000, v177
	v_add_f32_e32 v118, v118, v119
	v_mul_f32_e32 v119, v99, v99
	v_pk_fma_f32 v[100:101], v[100:101], 0.5, v[124:125] op_sel_hi:[1,0,1]
	v_fmac_f32_e32 v119, v98, v98
	v_add_f32_e32 v118, v119, v118
	v_mul_f32_e32 v119, v101, v101
	v_fmac_f32_e32 v119, v100, v100
	v_add_f32_e32 v118, v119, v118
	v_add_f32_e32 v122, v126, v118
	v_cvt_pk_bf16_f32 v118, v102, v103
	v_cvt_pk_bf16_f32 v119, v104, v105
	v_cvt_pk_bf16_f32 v120, v98, v99
	ds_bpermute_b32 v98, v145, v122
	v_add_co_u32_e32 v126, vcc, s2, v132
	v_cvt_pk_bf16_f32 v121, v100, v101
	s_mov_b32 s2, 0x90000
	s_nop 0
	v_addc_co_u32_e32 v127, vcc, 0, v133, vcc
	v_add_co_u32_e32 v128, vcc, s63, v132
	s_waitcnt lgkmcnt(0)
	v_add_f32_e32 v170, v122, v98
	v_addc_co_u32_e32 v129, vcc, 0, v133, vcc
	global_store_dwordx4 v146, v[106:109], s[26:27]
	global_store_dwordx4 v146, v[110:113], s[26:27] offset:256
	global_store_dwordx4 v[134:135], v[114:117], off
	global_store_dwordx4 v[134:135], v[118:121], off offset:256
	ds_bpermute_b32 v143, v144, v142
	ds_bpermute_b32 v171, v144, v170
	s_waitcnt vmcnt(12)
	v_lshlrev_b32_e32 v106, 16, v194
	v_and_b32_e32 v107, 0xffff0000, v194
	v_lshlrev_b32_e32 v108, 16, v195
	v_and_b32_e32 v109, 0xffff0000, v195
	v_lshlrev_b32_e32 v110, 16, v196
	v_and_b32_e32 v111, 0xffff0000, v196
	v_lshlrev_b32_e32 v112, 16, v197
	v_and_b32_e32 v113, 0xffff0000, v197
	v_pk_fma_f32 v[96:97], v[96:97], 0.5, v[108:109] op_sel_hi:[1,0,1]
	v_pk_fma_f32 v[94:95], v[94:95], 0.5, v[106:107] op_sel_hi:[1,0,1]
	v_pk_fma_f32 v[106:107], v[92:93], 0.5, v[112:113] op_sel_hi:[1,0,1]
	v_pk_fma_f32 v[92:93], v[90:91], 0.5, v[110:111] op_sel_hi:[1,0,1]
	v_mul_f32_e32 v90, v95, v95
	v_mul_f32_e32 v91, v97, v97
	v_fmac_f32_e32 v90, v94, v94
	v_fmac_f32_e32 v91, v96, v96
	v_add_f32_e32 v90, v90, v91
	v_mul_f32_e32 v91, v93, v93
	v_fmac_f32_e32 v91, v92, v92
	v_add_f32_e32 v90, v91, v90
	v_mul_f32_e32 v91, v107, v107
	v_fmac_f32_e32 v91, v106, v106
	v_add_f32_e32 v110, v91, v90
	v_cvt_pk_bf16_f32 v90, v94, v95
	v_cvt_pk_bf16_f32 v91, v96, v97
	v_lshlrev_b32_e32 v94, 16, v190
	v_and_b32_e32 v95, 0xffff0000, v190
	v_lshlrev_b32_e32 v96, 16, v191
	v_and_b32_e32 v97, 0xffff0000, v191
	v_cvt_pk_bf16_f32 v92, v92, v93
	v_cvt_pk_bf16_f32 v93, v106, v107
	v_lshlrev_b32_e32 v106, 16, v192
	v_and_b32_e32 v107, 0xffff0000, v192
	v_lshlrev_b32_e32 v108, 16, v193
	v_and_b32_e32 v109, 0xffff0000, v193
	v_pk_fma_f32 v[88:89], v[88:89], 0.5, v[96:97] op_sel_hi:[1,0,1]
	v_pk_fma_f32 v[86:87], v[86:87], 0.5, v[94:95] op_sel_hi:[1,0,1]
	v_pk_fma_f32 v[94:95], v[84:85], 0.5, v[108:109] op_sel_hi:[1,0,1]
	v_pk_fma_f32 v[84:85], v[82:83], 0.5, v[106:107] op_sel_hi:[1,0,1]
	v_mul_f32_e32 v82, v87, v87
	v_mul_f32_e32 v83, v89, v89
	v_fmac_f32_e32 v82, v86, v86
	v_fmac_f32_e32 v83, v88, v88
	v_add_f32_e32 v82, v82, v83
	v_mul_f32_e32 v83, v85, v85
	v_fmac_f32_e32 v83, v84, v84
	v_add_f32_e32 v82, v83, v82
	v_mul_f32_e32 v83, v95, v95
	v_fmac_f32_e32 v83, v94, v94
	v_add_f32_e32 v82, v83, v82
	v_add_f32_e32 v96, v82, v110
	v_cvt_pk_bf16_f32 v82, v86, v87
	ds_bpermute_b32 v86, v145, v96
	v_cvt_pk_bf16_f32 v83, v88, v89
	v_and_b32_e32 v87, 0xffff0000, v186
	v_lshlrev_b32_e32 v88, 16, v187
	v_and_b32_e32 v89, 0xffff0000, v187
	s_waitcnt lgkmcnt(0)
	v_add_f32_e32 v106, v96, v86
	v_lshlrev_b32_e32 v86, 16, v186
	v_cvt_pk_bf16_f32 v84, v84, v85
	v_cvt_pk_bf16_f32 v85, v94, v95
	v_lshlrev_b32_e32 v94, 16, v188
	v_and_b32_e32 v95, 0xffff0000, v188
	v_lshlrev_b32_e32 v96, 16, v189
	v_and_b32_e32 v97, 0xffff0000, v189
	v_pk_fma_f32 v[80:81], v[80:81], 0.5, v[88:89] op_sel_hi:[1,0,1]
	v_pk_fma_f32 v[78:79], v[78:79], 0.5, v[86:87] op_sel_hi:[1,0,1]
	v_pk_fma_f32 v[86:87], v[76:77], 0.5, v[96:97] op_sel_hi:[1,0,1]
	v_pk_fma_f32 v[76:77], v[74:75], 0.5, v[94:95] op_sel_hi:[1,0,1]
	v_mul_f32_e32 v74, v79, v79
	v_mul_f32_e32 v75, v81, v81
	v_fmac_f32_e32 v74, v78, v78
	v_fmac_f32_e32 v75, v80, v80
	v_add_f32_e32 v74, v74, v75
	v_mul_f32_e32 v75, v77, v77
	v_fmac_f32_e32 v75, v76, v76
	v_add_f32_e32 v74, v75, v74
	v_mul_f32_e32 v75, v87, v87
	v_fmac_f32_e32 v75, v86, v86
	v_add_f32_e32 v94, v75, v74
	v_cvt_pk_bf16_f32 v74, v78, v79
	v_cvt_pk_bf16_f32 v75, v80, v81
	v_lshlrev_b32_e32 v78, 16, v182
	v_and_b32_e32 v79, 0xffff0000, v182
	v_lshlrev_b32_e32 v80, 16, v183
	v_and_b32_e32 v81, 0xffff0000, v183
	v_pk_fma_f32 v[72:73], v[72:73], 0.5, v[80:81] op_sel_hi:[1,0,1]
	v_pk_fma_f32 v[70:71], v[70:71], 0.5, v[78:79] op_sel_hi:[1,0,1]
	v_cvt_pk_bf16_f32 v76, v76, v77
	v_cvt_pk_bf16_f32 v77, v86, v87
	v_lshlrev_b32_e32 v86, 16, v184
	v_and_b32_e32 v87, 0xffff0000, v184
	v_mul_f32_e32 v78, v71, v71
	v_mul_f32_e32 v79, v73, v73
	v_pk_fma_f32 v[66:67], v[66:67], 0.5, v[86:87] op_sel_hi:[1,0,1]
	v_fmac_f32_e32 v78, v70, v70
	v_fmac_f32_e32 v79, v72, v72
	v_lshlrev_b32_e32 v88, 16, v185
	v_and_b32_e32 v89, 0xffff0000, v185
	v_add_f32_e32 v78, v78, v79
	v_mul_f32_e32 v79, v67, v67
	v_pk_fma_f32 v[68:69], v[68:69], 0.5, v[88:89] op_sel_hi:[1,0,1]
	v_fmac_f32_e32 v79, v66, v66
	v_add_f32_e32 v78, v79, v78
	v_mul_f32_e32 v79, v69, v69
	v_fmac_f32_e32 v79, v68, v68
	v_add_f32_e32 v78, v79, v78
	v_add_f32_e32 v78, v78, v94
	v_cvt_pk_bf16_f32 v86, v70, v71
	v_cvt_pk_bf16_f32 v87, v72, v73
	v_cvt_pk_bf16_f32 v88, v66, v67
	ds_bpermute_b32 v66, v145, v78
	v_add_co_u32_e32 v98, vcc, s2, v132
	s_mov_b32 s2, 0x80000
	s_nop 0
	v_addc_co_u32_e32 v99, vcc, 0, v133, vcc
	v_add_co_u32_e32 v100, vcc, s2, v132
	v_cvt_pk_bf16_f32 v89, v68, v69
	s_waitcnt lgkmcnt(0)
	v_add_f32_e32 v102, v78, v66
	v_addc_co_u32_e32 v101, vcc, 0, v133, vcc
	global_store_dwordx4 v[128:129], v[90:93], off
	global_store_dwordx4 v[128:129], v[82:85], off offset:256
	global_store_dwordx4 v[126:127], v[74:77], off
	global_store_dwordx4 v[126:127], v[86:89], off offset:256
	s_mov_b32 s2, 0xb0000
	ds_bpermute_b32 v107, v144, v106
	ds_bpermute_b32 v103, v144, v102
	s_waitcnt vmcnt(12)
	v_lshlrev_b32_e32 v74, 16, v232
	v_and_b32_e32 v75, 0xffff0000, v232
	v_lshlrev_b32_e32 v76, 16, v233
	v_and_b32_e32 v77, 0xffff0000, v233
	v_lshlrev_b32_e32 v82, 16, v234
	v_and_b32_e32 v83, 0xffff0000, v234
	v_lshlrev_b32_e32 v84, 16, v235
	v_and_b32_e32 v85, 0xffff0000, v235
	v_pk_fma_f32 v[64:65], v[64:65], 0.5, v[76:77] op_sel_hi:[1,0,1]
	v_pk_fma_f32 v[62:63], v[62:63], 0.5, v[74:75] op_sel_hi:[1,0,1]
	v_pk_fma_f32 v[74:75], v[60:61], 0.5, v[84:85] op_sel_hi:[1,0,1]
	v_pk_fma_f32 v[60:61], v[58:59], 0.5, v[82:83] op_sel_hi:[1,0,1]
	v_mul_f32_e32 v58, v63, v63
	v_mul_f32_e32 v59, v65, v65
	v_fmac_f32_e32 v58, v62, v62
	v_fmac_f32_e32 v59, v64, v64
	v_add_f32_e32 v58, v58, v59
	v_mul_f32_e32 v59, v61, v61
	v_fmac_f32_e32 v59, v60, v60
	v_add_f32_e32 v58, v59, v58
	v_mul_f32_e32 v59, v75, v75
	v_fmac_f32_e32 v59, v74, v74
	v_add_f32_e32 v82, v59, v58
	v_cvt_pk_bf16_f32 v58, v62, v63
	v_cvt_pk_bf16_f32 v59, v64, v65
	v_lshlrev_b32_e32 v62, 16, v228
	v_and_b32_e32 v63, 0xffff0000, v228
	v_lshlrev_b32_e32 v64, 16, v229
	v_and_b32_e32 v65, 0xffff0000, v229
	v_cvt_pk_bf16_f32 v60, v60, v61
	v_cvt_pk_bf16_f32 v61, v74, v75
	v_lshlrev_b32_e32 v74, 16, v230
	v_and_b32_e32 v75, 0xffff0000, v230
	v_lshlrev_b32_e32 v76, 16, v231
	v_and_b32_e32 v77, 0xffff0000, v231
	v_pk_fma_f32 v[56:57], v[56:57], 0.5, v[64:65] op_sel_hi:[1,0,1]
	v_pk_fma_f32 v[54:55], v[54:55], 0.5, v[62:63] op_sel_hi:[1,0,1]
	v_pk_fma_f32 v[62:63], v[52:53], 0.5, v[76:77] op_sel_hi:[1,0,1]
	v_pk_fma_f32 v[52:53], v[50:51], 0.5, v[74:75] op_sel_hi:[1,0,1]
	v_mul_f32_e32 v50, v55, v55
	v_mul_f32_e32 v51, v57, v57
	v_fmac_f32_e32 v50, v54, v54
	v_fmac_f32_e32 v51, v56, v56
	v_add_f32_e32 v50, v50, v51
	v_mul_f32_e32 v51, v53, v53
	v_fmac_f32_e32 v51, v52, v52
	v_add_f32_e32 v50, v51, v50
	v_mul_f32_e32 v51, v63, v63
	v_fmac_f32_e32 v51, v62, v62
	v_add_f32_e32 v50, v51, v50
	v_add_f32_e32 v64, v50, v82
	v_cvt_pk_bf16_f32 v50, v54, v55
	ds_bpermute_b32 v54, v145, v64
	v_cvt_pk_bf16_f32 v51, v56, v57
	v_and_b32_e32 v55, 0xffff0000, v202
	v_lshlrev_b32_e32 v56, 16, v203
	v_and_b32_e32 v57, 0xffff0000, v203
	s_waitcnt lgkmcnt(0)
	v_add_f32_e32 v74, v64, v54
	v_lshlrev_b32_e32 v54, 16, v202
	v_cvt_pk_bf16_f32 v52, v52, v53
	v_cvt_pk_bf16_f32 v53, v62, v63
	v_lshlrev_b32_e32 v62, 16, v204
	v_and_b32_e32 v63, 0xffff0000, v204
	v_lshlrev_b32_e32 v64, 16, v205
	v_and_b32_e32 v65, 0xffff0000, v205
	v_pk_fma_f32 v[48:49], v[48:49], 0.5, v[56:57] op_sel_hi:[1,0,1]
	v_pk_fma_f32 v[46:47], v[46:47], 0.5, v[54:55] op_sel_hi:[1,0,1]
	v_pk_fma_f32 v[54:55], v[44:45], 0.5, v[64:65] op_sel_hi:[1,0,1]
	v_pk_fma_f32 v[44:45], v[42:43], 0.5, v[62:63] op_sel_hi:[1,0,1]
	v_mul_f32_e32 v42, v47, v47
	v_mul_f32_e32 v43, v49, v49
	v_fmac_f32_e32 v42, v46, v46
	v_fmac_f32_e32 v43, v48, v48
	v_add_f32_e32 v42, v42, v43
	v_mul_f32_e32 v43, v45, v45
	v_fmac_f32_e32 v43, v44, v44
	v_add_f32_e32 v42, v43, v42
	v_mul_f32_e32 v43, v55, v55
	v_fmac_f32_e32 v43, v54, v54
	v_add_f32_e32 v62, v43, v42
	v_cvt_pk_bf16_f32 v42, v46, v47
	v_cvt_pk_bf16_f32 v43, v48, v49
	v_lshlrev_b32_e32 v46, 16, v198
	v_and_b32_e32 v47, 0xffff0000, v198
	v_lshlrev_b32_e32 v48, 16, v199
	v_and_b32_e32 v49, 0xffff0000, v199
	v_pk_fma_f32 v[40:41], v[40:41], 0.5, v[48:49] op_sel_hi:[1,0,1]
	v_pk_fma_f32 v[38:39], v[38:39], 0.5, v[46:47] op_sel_hi:[1,0,1]
	v_cvt_pk_bf16_f32 v44, v44, v45
	v_cvt_pk_bf16_f32 v45, v54, v55
	v_lshlrev_b32_e32 v54, 16, v200
	v_and_b32_e32 v55, 0xffff0000, v200
	v_mul_f32_e32 v46, v39, v39
	v_mul_f32_e32 v47, v41, v41
	v_pk_fma_f32 v[34:35], v[34:35], 0.5, v[54:55] op_sel_hi:[1,0,1]
	v_fmac_f32_e32 v46, v38, v38
	v_fmac_f32_e32 v47, v40, v40
	v_lshlrev_b32_e32 v56, 16, v201
	v_and_b32_e32 v57, 0xffff0000, v201
	v_add_f32_e32 v46, v46, v47
	v_mul_f32_e32 v47, v35, v35
	v_pk_fma_f32 v[36:37], v[36:37], 0.5, v[56:57] op_sel_hi:[1,0,1]
	v_fmac_f32_e32 v47, v34, v34
	v_add_f32_e32 v46, v47, v46
	v_mul_f32_e32 v47, v37, v37
	v_fmac_f32_e32 v47, v36, v36
	v_add_f32_e32 v46, v47, v46
	v_add_f32_e32 v46, v46, v62
	v_cvt_pk_bf16_f32 v54, v38, v39
	v_cvt_pk_bf16_f32 v55, v40, v41
	v_cvt_pk_bf16_f32 v56, v34, v35
	ds_bpermute_b32 v34, v145, v46
	v_add_co_u32_e32 v66, vcc, s2, v132
	s_mov_b32 s2, 0xa0000
	s_nop 0
	v_addc_co_u32_e32 v67, vcc, 0, v133, vcc
	v_add_co_u32_e32 v68, vcc, s2, v132
	v_cvt_pk_bf16_f32 v57, v36, v37
	s_waitcnt lgkmcnt(0)
	v_add_f32_e32 v70, v46, v34
	v_addc_co_u32_e32 v69, vcc, 0, v133, vcc
	global_store_dwordx4 v[100:101], v[58:61], off
	global_store_dwordx4 v[100:101], v[50:53], off offset:256
	global_store_dwordx4 v[98:99], v[42:45], off
	global_store_dwordx4 v[98:99], v[54:57], off offset:256
	ds_bpermute_b32 v75, v144, v74
	ds_bpermute_b32 v71, v144, v70
	s_waitcnt vmcnt(12)
	v_lshlrev_b32_e32 v42, 16, v248
	v_and_b32_e32 v43, 0xffff0000, v248
	v_lshlrev_b32_e32 v44, 16, v249
	v_and_b32_e32 v45, 0xffff0000, v249
	v_lshlrev_b32_e32 v50, 16, v250
	v_and_b32_e32 v51, 0xffff0000, v250
	v_lshlrev_b32_e32 v52, 16, v251
	v_and_b32_e32 v53, 0xffff0000, v251
	v_pk_fma_f32 v[32:33], v[32:33], 0.5, v[44:45] op_sel_hi:[1,0,1]
	v_pk_fma_f32 v[30:31], v[30:31], 0.5, v[42:43] op_sel_hi:[1,0,1]
	v_pk_fma_f32 v[42:43], v[28:29], 0.5, v[52:53] op_sel_hi:[1,0,1]
	v_pk_fma_f32 v[28:29], v[26:27], 0.5, v[50:51] op_sel_hi:[1,0,1]
	v_mul_f32_e32 v26, v31, v31
	v_mul_f32_e32 v27, v33, v33
	v_fmac_f32_e32 v26, v30, v30
	v_fmac_f32_e32 v27, v32, v32
	v_add_f32_e32 v26, v26, v27
	v_mul_f32_e32 v27, v29, v29
	v_fmac_f32_e32 v27, v28, v28
	v_add_f32_e32 v26, v27, v26
	v_mul_f32_e32 v27, v43, v43
	v_fmac_f32_e32 v27, v42, v42
	v_add_f32_e32 v50, v27, v26
	v_cvt_pk_bf16_f32 v26, v30, v31
	v_cvt_pk_bf16_f32 v27, v32, v33
	v_lshlrev_b32_e32 v30, 16, v244
	v_and_b32_e32 v31, 0xffff0000, v244
	v_lshlrev_b32_e32 v32, 16, v245
	v_and_b32_e32 v33, 0xffff0000, v245
	v_lshlrev_b32_e32 v44, 16, v247
	v_and_b32_e32 v45, 0xffff0000, v247
	v_pk_fma_f32 v[24:25], v[24:25], 0.5, v[32:33] op_sel_hi:[1,0,1]
	v_pk_fma_f32 v[22:23], v[22:23], 0.5, v[30:31] op_sel_hi:[1,0,1]
	v_cvt_pk_bf16_f32 v28, v28, v29
	v_cvt_pk_bf16_f32 v29, v42, v43
	v_lshlrev_b32_e32 v42, 16, v246
	v_and_b32_e32 v43, 0xffff0000, v246
	v_pk_fma_f32 v[30:31], v[20:21], 0.5, v[44:45] op_sel_hi:[1,0,1]
	v_mul_f32_e32 v20, v23, v23
	v_mul_f32_e32 v21, v25, v25
	v_pk_fma_f32 v[18:19], v[18:19], 0.5, v[42:43] op_sel_hi:[1,0,1]
	v_fmac_f32_e32 v20, v22, v22
	v_fmac_f32_e32 v21, v24, v24
	v_add_f32_e32 v20, v20, v21
	v_mul_f32_e32 v21, v19, v19
	v_fmac_f32_e32 v21, v18, v18
	v_add_f32_e32 v20, v21, v20
	v_mul_f32_e32 v21, v31, v31
	v_fmac_f32_e32 v21, v30, v30
	v_add_f32_e32 v20, v21, v20
	v_add_f32_e32 v32, v20, v50
	v_cvt_pk_bf16_f32 v20, v22, v23
	v_cvt_pk_bf16_f32 v21, v24, v25
	v_cvt_pk_bf16_f32 v22, v18, v19
	ds_bpermute_b32 v18, v145, v32
	v_cvt_pk_bf16_f32 v23, v30, v31
	v_lshlrev_b32_e32 v24, 16, v240
	v_and_b32_e32 v25, 0xffff0000, v240
	v_lshlrev_b32_e32 v30, 16, v241
	v_and_b32_e32 v31, 0xffff0000, v241
	s_waitcnt lgkmcnt(0)
	v_add_f32_e32 v18, v32, v18
	v_lshlrev_b32_e32 v32, 16, v242
	v_and_b32_e32 v33, 0xffff0000, v242
	v_lshlrev_b32_e32 v38, 16, v243
	v_and_b32_e32 v39, 0xffff0000, v243
	v_pk_fma_f32 v[16:17], v[16:17], 0.5, v[30:31] op_sel_hi:[1,0,1]
	v_pk_fma_f32 v[14:15], v[14:15], 0.5, v[24:25] op_sel_hi:[1,0,1]
	v_pk_fma_f32 v[24:25], v[12:13], 0.5, v[38:39] op_sel_hi:[1,0,1]
	v_pk_fma_f32 v[12:13], v[10:11], 0.5, v[32:33] op_sel_hi:[1,0,1]
	v_mul_f32_e32 v10, v15, v15
	v_mul_f32_e32 v11, v17, v17
	v_fmac_f32_e32 v10, v14, v14
	v_fmac_f32_e32 v11, v16, v16
	v_add_f32_e32 v10, v10, v11
	v_mul_f32_e32 v11, v13, v13
	v_fmac_f32_e32 v11, v12, v12
	v_add_f32_e32 v10, v11, v10
	v_mul_f32_e32 v11, v25, v25
	v_fmac_f32_e32 v11, v24, v24
	v_add_f32_e32 v32, v11, v10
	v_cvt_pk_bf16_f32 v10, v14, v15
	v_cvt_pk_bf16_f32 v11, v16, v17
	v_lshlrev_b32_e32 v14, 16, v236
	v_and_b32_e32 v15, 0xffff0000, v236
	v_lshlrev_b32_e32 v16, 16, v237
	v_and_b32_e32 v17, 0xffff0000, v237
	v_lshlrev_b32_e32 v30, 16, v239
	v_and_b32_e32 v31, 0xffff0000, v239
	v_pk_fma_f32 v[8:9], v[8:9], 0.5, v[16:17] op_sel_hi:[1,0,1]
	v_pk_fma_f32 v[6:7], v[6:7], 0.5, v[14:15] op_sel_hi:[1,0,1]
	v_cvt_pk_bf16_f32 v12, v12, v13
	v_cvt_pk_bf16_f32 v13, v24, v25
	v_lshlrev_b32_e32 v24, 16, v238
	v_and_b32_e32 v25, 0xffff0000, v238
	v_pk_fma_f32 v[14:15], v[4:5], 0.5, v[30:31] op_sel_hi:[1,0,1]
	v_mul_f32_e32 v4, v7, v7
	v_mul_f32_e32 v5, v9, v9
	v_pk_fma_f32 v[2:3], v[2:3], 0.5, v[24:25] op_sel_hi:[1,0,1]
	v_fmac_f32_e32 v4, v6, v6
	v_fmac_f32_e32 v5, v8, v8
	v_add_f32_e32 v4, v4, v5
	v_mul_f32_e32 v5, v3, v3
	v_fmac_f32_e32 v5, v2, v2
	v_add_f32_e32 v4, v5, v4
	v_mul_f32_e32 v5, v15, v15
	v_fmac_f32_e32 v5, v14, v14
	v_add_f32_e32 v4, v5, v4
	v_add_f32_e32 v16, v4, v32
	v_cvt_pk_bf16_f32 v4, v6, v7
	v_cvt_pk_bf16_f32 v5, v8, v9
	v_cvt_pk_bf16_f32 v6, v2, v3
	ds_bpermute_b32 v2, v145, v16
	ds_bpermute_b32 v19, v144, v18
	v_cvt_pk_bf16_f32 v7, v14, v15
	global_store_dwordx4 v[68:69], v[26:29], off
	global_store_dwordx4 v[68:69], v[20:23], off offset:256
	global_store_dwordx4 v[66:67], v[10:13], off
	global_store_dwordx4 v[66:67], v[4:7], off offset:256
	s_waitcnt lgkmcnt(1)
	v_add_f32_e32 v2, v16, v2
	ds_bpermute_b32 v3, v144, v2
	s_and_saveexec_b64 s[8:9], s[40:41]
	s_cbranch_execz .LBB0_2161
	v_add_f32_e32 v4, v142, v143
	v_fma_f32 v4, v4, s11, 0.5
	v_trunc_f32_e32 v4, v4
	v_mul_f32_e32 v5, 0x2f800000, v4
	v_floor_f32_e32 v5, v5
	v_fmac_f32_e32 v4, 0xcf800000, v5
	v_cvt_u32_f32_e32 v4, v4
	v_cvt_u32_f32_e32 v5, v5
	s_waitcnt lgkmcnt(0)
	v_add_f32_e32 v6, v2, v3
	v_add_f32_e32 v12, v170, v171
	v_lshl_add_u64 v[2:3], s[46:47], 3, v[130:131]
	global_atomic_add_x2 v[2:3], v[4:5], off
	v_fma_f32 v4, v12, s11, 0.5
	v_trunc_f32_e32 v4, v4
	v_mul_f32_e32 v5, 0x2f800000, v4
	v_floor_f32_e32 v5, v5
	v_fmac_f32_e32 v4, 0xcf800000, v5
	v_cvt_u32_f32_e32 v4, v4
	v_cvt_u32_f32_e32 v5, v5
	v_add_f32_e32 v11, v106, v107
	v_add_f32_e32 v10, v102, v103
	v_add_f32_e32 v9, v74, v75
	global_atomic_add_x2 v[2:3], v[4:5], off offset:128
	v_fma_f32 v4, v11, s11, 0.5
	v_trunc_f32_e32 v4, v4
	v_mul_f32_e32 v5, 0x2f800000, v4
	v_floor_f32_e32 v5, v5
	v_fmac_f32_e32 v4, 0xcf800000, v5
	v_cvt_u32_f32_e32 v4, v4
	v_cvt_u32_f32_e32 v5, v5
	v_add_f32_e32 v8, v70, v71
	v_add_f32_e32 v7, v18, v19
	global_atomic_add_x2 v[2:3], v[4:5], off offset:256
	v_fma_f32 v4, v10, s11, 0.5
	v_trunc_f32_e32 v4, v4
	v_mul_f32_e32 v5, 0x2f800000, v4
	v_floor_f32_e32 v5, v5
	v_fmac_f32_e32 v4, 0xcf800000, v5
	v_cvt_u32_f32_e32 v4, v4
	v_cvt_u32_f32_e32 v5, v5
	global_atomic_add_x2 v[2:3], v[4:5], off offset:384
	v_fma_f32 v4, v9, s11, 0.5
	v_trunc_f32_e32 v4, v4
	v_mul_f32_e32 v5, 0x2f800000, v4
	v_floor_f32_e32 v5, v5
	v_fmac_f32_e32 v4, 0xcf800000, v5
	v_cvt_u32_f32_e32 v4, v4
	v_cvt_u32_f32_e32 v5, v5
	global_atomic_add_x2 v[2:3], v[4:5], off offset:1024
	v_fma_f32 v4, v8, s11, 0.5
	v_trunc_f32_e32 v4, v4
	v_mul_f32_e32 v5, 0x2f800000, v4
	v_floor_f32_e32 v5, v5
	v_fmac_f32_e32 v4, 0xcf800000, v5
	v_cvt_u32_f32_e32 v4, v4
	v_cvt_u32_f32_e32 v5, v5
	global_atomic_add_x2 v[2:3], v[4:5], off offset:1152
	v_fma_f32 v4, v7, s11, 0.5
	v_trunc_f32_e32 v4, v4
	v_mul_f32_e32 v5, 0x2f800000, v4
	v_floor_f32_e32 v5, v5
	v_fmac_f32_e32 v4, 0xcf800000, v5
	v_cvt_u32_f32_e32 v4, v4
	v_cvt_u32_f32_e32 v5, v5
	global_atomic_add_x2 v[2:3], v[4:5], off offset:1280
	v_fma_f32 v4, v6, s11, 0.5
	v_trunc_f32_e32 v4, v4
	v_mul_f32_e32 v5, 0x2f800000, v4
	v_floor_f32_e32 v5, v5
	v_fmac_f32_e32 v4, 0xcf800000, v5
	v_cvt_u32_f32_e32 v4, v4
	v_cvt_u32_f32_e32 v5, v5
	global_atomic_add_x2 v[2:3], v[4:5], off offset:1408
